# strategy 4 in the GEMM tile epilogues: wave group 0 raised to priority 1 for the epilogue (both groups run it at once), on top of the attention raise
# baseline (speedup 1.0000x reference)
; #define PG8_STAGE(bufoff, gbase, voff) do { _Pragma("unroll") for (int _i = 0; _i < 2; ++_i) \
;         __builtin_amdgcn_global_load_lds((const unsigned*)((const char*)(gbase) + (voff)[_i]), (LAS unsigned*)(lds + (bufoff) + ldsw + _i * 8192), 16, 0, 0); } while (0)
; #define PG8_LDA(dst, b, h) do { _Pragma("unroll") for (int m = 0; m < 4; ++m) _Pragma("unroll") for (int k = 0; k < 2; ++k) dst[m][k] = *(const LAS bf16x8*)(lds + PG8_SA(b, h) + aoff + m * 2048 + k * 1024); } while (0)
; #define PG8_LDB(dst, b, h) do { _Pragma("unroll") for (int n = 0; n < 2; ++n) _Pragma("unroll") for (int k = 0; k < 2; ++k) dst[n][k] = *(const LAS bf16x8*)(lds + PG8_SB(b, h) + boff + n * 2048 + k * 1024); } while (0)
; #define PG8_MMA(ai, bj, At, Bt) do { __builtin_amdgcn_s_setprio(1); _Pragma("unroll") for (int m = 0; m < 4; ++m) _Pragma("unroll") for (int n = 0; n < 2; ++n) _Pragma("unroll") for (int k = 0; k < 2; ++k) \
;         acc[ai][bj][m][n] = __builtin_amdgcn_mfma_f32_16x16x32_bf16(Bt[n][k], At[m][k], acc[ai][bj][m][n], 0, 0, 0); __builtin_amdgcn_s_setprio(0); } while (0)
; template <class Epi, class Sched, bool ALIGN_EPI = false, bool SP2 = false>
; __device__ __forceinline__ void gemm_phase(LAS unsigned char* lds, const Gemm g, const Sched& S, const Epi& E) {
;     ...
;         const char* nA = has_next ? (const char*)g.A + (size_t)nxt.pm * tstep : cA; const char* nB = has_next ? (const char*)g.Bt + (size_t)nxt.pn * tstep : cB;
;         for (int t = 0; t < nt; t += 2) {
;             const bool last = (t == nt - 2);
;             const char* a1 = cA + (size_t)(t + 1) * kstep;
;             const char* a2 = last ? nA : cA + (size_t)(t + 2) * kstep; const char* b2 = last ? nB : cB + (size_t)(t + 2) * kstep;
;             const char* a3 = a2 + kstep; const char* b3 = b2 + kstep;
;             if (last && has_next) S.a_ready(nxt);
;             if constexpr (SP2) {
;             PG8_LDB(B0, 0, 0); PG8_LDB(B1, 0, 1); PG8_SCHED; PG8_LDA(At, 0, 0); PG8_STAGE(PG8_SA(1, 1), a1 + hstep, voffA);
;             PG8_WAIT_V(8); PG8_WAIT_L(0); PG8_BAR; PG8_MMA(0, 0, At, B0); PG8_MMA(0, 1, At, B1); PG8_BAR; PG8_SCHED;
;             PG8_LDA(At, 0, 1); PG8_STAGE(PG8_SB(0, 0), b2, voffB); PG8_STAGE(PG8_SB(0, 1), b2 + hstep, voffB); PG8_STAGE(PG8_SA(0, 0), a2, voffA);
;             PG8_WAIT_V(8); PG8_WAIT_L(0); PG8_BAR; PG8_MMA(1, 0, At, B0); PG8_MMA(1, 1, At, B1); PG8_BAR; PG8_SCHED;
.LBB0_173:
	s_add_u32 s26, s24, 0xfff80080
	s_addc_u32 s27, s25, -1
	s_add_i32 s45, 0, 0x10000
	s_cmp_eq_u32 s44, 28
	s_cselect_b32 s29, s7, s27
	s_cselect_b32 s28, s8, s26
	v_add_u32_e32 v140, s45, v145
	s_cselect_b32 s27, s17, s43
	s_cselect_b32 s26, s19, s35
	s_add_i32 s47, 0, 0x14000
	ds_read_b128 v[150:153], v140
	ds_read_b128 v[154:157], v140 offset:1024
	ds_read_b128 v[158:161], v140 offset:2048
	ds_read_b128 v[162:165], v140 offset:3072
	v_add_u32_e32 v140, s47, v145
	ds_read_b128 v[166:169], v140
	ds_read_b128 v[170:173], v140 offset:1024
	ds_read_b128 v[174:177], v140 offset:2048
	ds_read_b128 v[178:181], v140 offset:3072
	v_lshl_add_u64 v[140:141], s[24:25], 0, v[136:137]
	s_add_i32 m0, s30, 0xc000
	ds_read_b128 v[182:185], v149
	ds_read_b128 v[194:197], v149 offset:1024
	ds_read_b128 v[198:201], v149 offset:2048
	ds_read_b128 v[202:205], v149 offset:3072
	ds_read_b128 v[206:209], v149 offset:4096
	ds_read_b128 v[210:213], v149 offset:5120
	ds_read_b128 v[214:217], v149 offset:6144
	ds_read_b128 v[218:221], v149 offset:7168
	global_load_lds_dwordx4 v[140:141], off
	v_lshl_add_u64 v[140:141], s[24:25], 0, v[138:139]
	s_add_i32 m0, s30, 0xe000
	s_nop 0
	global_load_lds_dwordx4 v[140:141], off
	s_waitcnt vmcnt(8)
	s_waitcnt lgkmcnt(0)
	s_setprio 1
	s_barrier
	v_mfma_f32_16x16x32_bf16 v[126:129], v[150:153], v[182:185], v[126:129]
	v_mfma_f32_16x16x32_bf16 v[126:129], v[154:157], v[194:197], v[126:129]
	v_mfma_f32_16x16x32_bf16 v[122:125], v[158:161], v[182:185], v[122:125]
	v_mfma_f32_16x16x32_bf16 v[122:125], v[162:165], v[194:197], v[122:125]
	v_mfma_f32_16x16x32_bf16 v[106:109], v[158:161], v[198:201], v[106:109]
	v_mfma_f32_16x16x32_bf16 v[106:109], v[162:165], v[202:205], v[106:109]
	v_mfma_f32_16x16x32_bf16 v[110:113], v[150:153], v[198:201], v[110:113]
	v_mfma_f32_16x16x32_bf16 v[110:113], v[154:157], v[202:205], v[110:113]
	v_mfma_f32_16x16x32_bf16 v[94:97], v[150:153], v[206:209], v[94:97]
	v_mfma_f32_16x16x32_bf16 v[94:97], v[154:157], v[210:213], v[94:97]
	v_mfma_f32_16x16x32_bf16 v[90:93], v[158:161], v[206:209], v[90:93]
	v_mfma_f32_16x16x32_bf16 v[90:93], v[162:165], v[210:213], v[90:93]
	v_mfma_f32_16x16x32_bf16 v[74:77], v[158:161], v[214:217], v[74:77]
	v_mfma_f32_16x16x32_bf16 v[74:77], v[162:165], v[218:221], v[74:77]
	v_mfma_f32_16x16x32_bf16 v[78:81], v[150:153], v[214:217], v[78:81]
	v_mfma_f32_16x16x32_bf16 v[78:81], v[154:157], v[218:221], v[78:81]
	v_mfma_f32_16x16x32_bf16 v[118:121], v[166:169], v[182:185], v[118:121]
	v_mfma_f32_16x16x32_bf16 v[118:121], v[170:173], v[194:197], v[118:121]
	v_mfma_f32_16x16x32_bf16 v[114:117], v[174:177], v[182:185], v[114:117]
	v_mfma_f32_16x16x32_bf16 v[114:117], v[178:181], v[194:197], v[114:117]
	v_mfma_f32_16x16x32_bf16 v[98:101], v[174:177], v[198:201], v[98:101]
	v_mfma_f32_16x16x32_bf16 v[98:101], v[178:181], v[202:205], v[98:101]
	v_mfma_f32_16x16x32_bf16 v[102:105], v[166:169], v[198:201], v[102:105]
	v_mfma_f32_16x16x32_bf16 v[102:105], v[170:173], v[202:205], v[102:105]
	v_mfma_f32_16x16x32_bf16 v[86:89], v[166:169], v[206:209], v[86:89]
	v_mfma_f32_16x16x32_bf16 v[86:89], v[170:173], v[210:213], v[86:89]
	v_mfma_f32_16x16x32_bf16 v[82:85], v[174:177], v[206:209], v[82:85]
	v_mfma_f32_16x16x32_bf16 v[82:85], v[178:181], v[210:213], v[82:85]
	v_mfma_f32_16x16x32_bf16 v[66:69], v[174:177], v[214:217], v[66:69]
	v_mfma_f32_16x16x32_bf16 v[66:69], v[178:181], v[218:221], v[66:69]
	v_mfma_f32_16x16x32_bf16 v[70:73], v[166:169], v[214:217], v[70:73]
	v_mfma_f32_16x16x32_bf16 v[70:73], v[170:173], v[218:221], v[70:73]
	s_barrier
	s_setprio 0
	s_add_i32 s45, s45, s9
	v_lshl_add_u64 v[140:141], s[26:27], 0, v[0:1]
	s_mov_b32 m0, s45
	ds_read_b128 v[182:185], v149 offset:16384
	ds_read_b128 v[194:197], v149 offset:17408
	ds_read_b128 v[198:201], v149 offset:18432
	ds_read_b128 v[202:205], v149 offset:19456
	ds_read_b128 v[206:209], v149 offset:20480
	ds_read_b128 v[210:213], v149 offset:21504
	ds_read_b128 v[214:217], v149 offset:22528
	ds_read_b128 v[218:221], v149 offset:23552
	global_load_lds_dwordx4 v[140:141], off
	s_add_i32 m0, s45, 0x2000
	s_add_u32 s48, s26, 0x80000
	v_lshl_add_u64 v[186:187], s[26:27], 0, v[130:131]
	s_addc_u32 s49, s27, 0
	s_add_i32 s45, s47, s9
	global_load_lds_dwordx4 v[186:187], off
	v_lshl_add_u64 v[188:189], s[48:49], 0, v[0:1]
	s_mov_b32 m0, s45
	v_lshl_add_u64 v[190:191], s[28:29], 0, v[132:133]
	global_load_lds_dwordx4 v[188:189], off
	v_lshl_add_u64 v[188:189], s[48:49], 0, v[130:131]
	s_add_i32 m0, s45, 0x2000
	s_nop 0
	global_load_lds_dwordx4 v[188:189], off
	v_lshl_add_u64 v[188:189], s[28:29], 0, v[134:135]
	s_mov_b32 m0, s30
	s_nop 0
	global_load_lds_dwordx4 v[188:189], off
	s_mov_b32 m0, s31
	s_nop 0
	global_load_lds_dwordx4 v[190:191], off
	s_waitcnt vmcnt(8)
	s_waitcnt lgkmcnt(0)
	s_setprio 1
	s_barrier
; #define PG8_STAGE(bufoff, gbase, voff) do { _Pragma("unroll") for (int _i = 0; _i < 2; ++_i) \
;         __builtin_amdgcn_global_load_lds((const unsigned*)((const char*)(gbase) + (voff)[_i]), (LAS unsigned*)(lds + (bufoff) + ldsw + _i * 8192), 16, 0, 0); } while (0)
; #define PG8_LDA(dst, b, h) do { _Pragma("unroll") for (int m = 0; m < 4; ++m) _Pragma("unroll") for (int k = 0; k < 2; ++k) dst[m][k] = *(const LAS bf16x8*)(lds + PG8_SA(b, h) + aoff + m * 2048 + k * 1024); } while (0)
; #define PG8_LDB(dst, b, h) do { _Pragma("unroll") for (int n = 0; n < 2; ++n) _Pragma("unroll") for (int k = 0; k < 2; ++k) dst[n][k] = *(const LAS bf16x8*)(lds + PG8_SB(b, h) + boff + n * 2048 + k * 1024); } while (0)
; #define PG8_MMA(ai, bj, At, Bt) do { __builtin_amdgcn_s_setprio(1); _Pragma("unroll") for (int m = 0; m < 4; ++m) _Pragma("unroll") for (int n = 0; n < 2; ++n) _Pragma("unroll") for (int k = 0; k < 2; ++k) \
;         acc[ai][bj][m][n] = __builtin_amdgcn_mfma_f32_16x16x32_bf16(Bt[n][k], At[m][k], acc[ai][bj][m][n], 0, 0, 0); __builtin_amdgcn_s_setprio(0); } while (0)
; #define PG8_WAIT_V(n) asm volatile("s_waitcnt vmcnt(" #n ")" ::: "memory")
; #define PG8_WAIT_L(n) asm volatile("s_waitcnt lgkmcnt(" #n ")" ::: "memory")
; #define PG8_BAR __builtin_amdgcn_s_barrier()
; #define PG8_SCHED __builtin_amdgcn_sched_barrier(0)
; template <class Epi, class Sched, bool ALIGN_EPI = false, bool SP2 = false>
; __device__ __forceinline__ void gemm_phase(LAS unsigned char* lds, const Gemm g, const Sched& S, const Epi& E) {
;     ...
;             PG8_WAIT_V(8); PG8_WAIT_L(0); PG8_BAR; PG8_MMA(1, 0, At, B0); PG8_MMA(1, 1, At, B1); PG8_BAR; PG8_SCHED;
;             PG8_LDB(B0, 1, 0); PG8_LDB(B1, 1, 1); PG8_SCHED; PG8_LDA(At, 1, 0); PG8_STAGE(PG8_SA(0, 1), a2 + hstep, voffA);
;             PG8_WAIT_V(8); PG8_WAIT_L(0); PG8_BAR; PG8_MMA(0, 0, At, B0); PG8_MMA(0, 1, At, B1); PG8_BAR; PG8_SCHED;
	v_mfma_f32_16x16x32_bf16 v[62:65], v[150:153], v[182:185], v[62:65]
	v_mfma_f32_16x16x32_bf16 v[62:65], v[154:157], v[194:197], v[62:65]
	v_mfma_f32_16x16x32_bf16 v[58:61], v[158:161], v[182:185], v[58:61]
	v_mfma_f32_16x16x32_bf16 v[58:61], v[162:165], v[194:197], v[58:61]
	v_mfma_f32_16x16x32_bf16 v[42:45], v[158:161], v[198:201], v[42:45]
	v_mfma_f32_16x16x32_bf16 v[42:45], v[162:165], v[202:205], v[42:45]
	v_mfma_f32_16x16x32_bf16 v[46:49], v[150:153], v[198:201], v[46:49]
	v_mfma_f32_16x16x32_bf16 v[46:49], v[154:157], v[202:205], v[46:49]
	v_mfma_f32_16x16x32_bf16 v[30:33], v[150:153], v[206:209], v[30:33]
	v_mfma_f32_16x16x32_bf16 v[30:33], v[154:157], v[210:213], v[30:33]
	v_mfma_f32_16x16x32_bf16 v[26:29], v[158:161], v[206:209], v[26:29]
	v_mfma_f32_16x16x32_bf16 v[26:29], v[162:165], v[210:213], v[26:29]
	v_mfma_f32_16x16x32_bf16 v[10:13], v[158:161], v[214:217], v[10:13]
	v_mfma_f32_16x16x32_bf16 v[10:13], v[162:165], v[218:221], v[10:13]
	v_mfma_f32_16x16x32_bf16 v[14:17], v[150:153], v[214:217], v[14:17]
	v_mfma_f32_16x16x32_bf16 v[14:17], v[154:157], v[218:221], v[14:17]
	v_mfma_f32_16x16x32_bf16 v[54:57], v[166:169], v[182:185], v[54:57]
	v_mfma_f32_16x16x32_bf16 v[54:57], v[170:173], v[194:197], v[54:57]
	v_mfma_f32_16x16x32_bf16 v[50:53], v[174:177], v[182:185], v[50:53]
	v_mfma_f32_16x16x32_bf16 v[50:53], v[178:181], v[194:197], v[50:53]
	v_mfma_f32_16x16x32_bf16 v[34:37], v[174:177], v[198:201], v[34:37]
	v_mfma_f32_16x16x32_bf16 v[34:37], v[178:181], v[202:205], v[34:37]
	v_mfma_f32_16x16x32_bf16 v[38:41], v[166:169], v[198:201], v[38:41]
	v_mfma_f32_16x16x32_bf16 v[38:41], v[170:173], v[202:205], v[38:41]
	v_mfma_f32_16x16x32_bf16 v[22:25], v[166:169], v[206:209], v[22:25]
	v_mfma_f32_16x16x32_bf16 v[22:25], v[170:173], v[210:213], v[22:25]
	v_mfma_f32_16x16x32_bf16 v[18:21], v[174:177], v[206:209], v[18:21]
	v_mfma_f32_16x16x32_bf16 v[18:21], v[178:181], v[210:213], v[18:21]
	v_mfma_f32_16x16x32_bf16 v[2:5], v[174:177], v[214:217], v[2:5]
	v_mfma_f32_16x16x32_bf16 v[2:5], v[178:181], v[218:221], v[2:5]
	v_mfma_f32_16x16x32_bf16 v[6:9], v[166:169], v[214:217], v[6:9]
	v_mfma_f32_16x16x32_bf16 v[6:9], v[170:173], v[218:221], v[6:9]
	s_barrier
	s_setprio 0
	s_add_i32 s45, 0, 0x18000
	v_add_u32_e32 v142, s45, v145
	s_add_i32 s47, 0, 0x1c000
	ds_read_b128 v[150:153], v142
	ds_read_b128 v[154:157], v142 offset:1024
	ds_read_b128 v[158:161], v142 offset:2048
	ds_read_b128 v[162:165], v142 offset:3072
	v_add_u32_e32 v142, s47, v145
	ds_read_b128 v[166:169], v142
	ds_read_b128 v[170:173], v142 offset:1024
	ds_read_b128 v[174:177], v142 offset:2048
	ds_read_b128 v[178:181], v142 offset:3072
	s_add_u32 s28, s28, 0x80000
	s_addc_u32 s29, s29, 0
	s_mov_b32 m0, s38
	v_lshl_add_u64 v[192:193], s[28:29], 0, v[134:135]
	ds_read_b128 v[182:185], v149 offset:32768
	ds_read_b128 v[194:197], v149 offset:33792
	ds_read_b128 v[198:201], v149 offset:34816
	ds_read_b128 v[202:205], v149 offset:35840
	ds_read_b128 v[206:209], v149 offset:36864
	ds_read_b128 v[210:213], v149 offset:37888
	ds_read_b128 v[214:217], v149 offset:38912
	ds_read_b128 v[218:221], v149 offset:39936
	global_load_lds_dwordx4 v[192:193], off
	v_lshl_add_u64 v[192:193], s[28:29], 0, v[132:133]
	s_mov_b32 m0, s39
	s_nop 0
	global_load_lds_dwordx4 v[192:193], off
	s_waitcnt vmcnt(8)
	s_waitcnt lgkmcnt(0)
	s_setprio 1
	s_barrier
	v_mfma_f32_16x16x32_bf16 v[126:129], v[150:153], v[182:185], v[126:129]
	v_mfma_f32_16x16x32_bf16 v[126:129], v[154:157], v[194:197], v[126:129]
	v_mfma_f32_16x16x32_bf16 v[122:125], v[158:161], v[182:185], v[122:125]
	v_mfma_f32_16x16x32_bf16 v[122:125], v[162:165], v[194:197], v[122:125]
	v_mfma_f32_16x16x32_bf16 v[106:109], v[158:161], v[198:201], v[106:109]
	v_mfma_f32_16x16x32_bf16 v[106:109], v[162:165], v[202:205], v[106:109]
	v_mfma_f32_16x16x32_bf16 v[110:113], v[150:153], v[198:201], v[110:113]
	v_mfma_f32_16x16x32_bf16 v[110:113], v[154:157], v[202:205], v[110:113]
	v_mfma_f32_16x16x32_bf16 v[94:97], v[150:153], v[206:209], v[94:97]
	v_mfma_f32_16x16x32_bf16 v[94:97], v[154:157], v[210:213], v[94:97]
	v_mfma_f32_16x16x32_bf16 v[90:93], v[158:161], v[206:209], v[90:93]
	v_mfma_f32_16x16x32_bf16 v[90:93], v[162:165], v[210:213], v[90:93]
	v_mfma_f32_16x16x32_bf16 v[74:77], v[158:161], v[214:217], v[74:77]
	v_mfma_f32_16x16x32_bf16 v[74:77], v[162:165], v[218:221], v[74:77]
	v_mfma_f32_16x16x32_bf16 v[78:81], v[150:153], v[214:217], v[78:81]
	v_mfma_f32_16x16x32_bf16 v[78:81], v[154:157], v[218:221], v[78:81]
	v_mfma_f32_16x16x32_bf16 v[118:121], v[166:169], v[182:185], v[118:121]
	v_mfma_f32_16x16x32_bf16 v[118:121], v[170:173], v[194:197], v[118:121]
	v_mfma_f32_16x16x32_bf16 v[114:117], v[174:177], v[182:185], v[114:117]
	v_mfma_f32_16x16x32_bf16 v[114:117], v[178:181], v[194:197], v[114:117]
	v_mfma_f32_16x16x32_bf16 v[98:101], v[174:177], v[198:201], v[98:101]
	v_mfma_f32_16x16x32_bf16 v[98:101], v[178:181], v[202:205], v[98:101]
	v_mfma_f32_16x16x32_bf16 v[102:105], v[166:169], v[198:201], v[102:105]
	v_mfma_f32_16x16x32_bf16 v[102:105], v[170:173], v[202:205], v[102:105]
	v_mfma_f32_16x16x32_bf16 v[86:89], v[166:169], v[206:209], v[86:89]
	v_mfma_f32_16x16x32_bf16 v[86:89], v[170:173], v[210:213], v[86:89]
	v_mfma_f32_16x16x32_bf16 v[82:85], v[174:177], v[206:209], v[82:85]
	v_mfma_f32_16x16x32_bf16 v[82:85], v[178:181], v[210:213], v[82:85]
	v_mfma_f32_16x16x32_bf16 v[66:69], v[174:177], v[214:217], v[66:69]
	v_mfma_f32_16x16x32_bf16 v[66:69], v[178:181], v[218:221], v[66:69]
	v_mfma_f32_16x16x32_bf16 v[70:73], v[166:169], v[214:217], v[70:73]
	v_mfma_f32_16x16x32_bf16 v[70:73], v[170:173], v[218:221], v[70:73]
	s_barrier
; #define PG8_STAGE(bufoff, gbase, voff) do { _Pragma("unroll") for (int _i = 0; _i < 2; ++_i) \
;         __builtin_amdgcn_global_load_lds((const unsigned*)((const char*)(gbase) + (voff)[_i]), (LAS unsigned*)(lds + (bufoff) + ldsw + _i * 8192), 16, 0, 0); } while (0)
; #define PG8_LDA(dst, b, h) do { _Pragma("unroll") for (int m = 0; m < 4; ++m) _Pragma("unroll") for (int k = 0; k < 2; ++k) dst[m][k] = *(const LAS bf16x8*)(lds + PG8_SA(b, h) + aoff + m * 2048 + k * 1024); } while (0)
; #define PG8_MMA(ai, bj, At, Bt) do { __builtin_amdgcn_s_setprio(1); _Pragma("unroll") for (int m = 0; m < 4; ++m) _Pragma("unroll") for (int n = 0; n < 2; ++n) _Pragma("unroll") for (int k = 0; k < 2; ++k) \
;         acc[ai][bj][m][n] = __builtin_amdgcn_mfma_f32_16x16x32_bf16(Bt[n][k], At[m][k], acc[ai][bj][m][n], 0, 0, 0); __builtin_amdgcn_s_setprio(0); } while (0)
; #define PG8_WAIT_V(n) asm volatile("s_waitcnt vmcnt(" #n ")" ::: "memory")
; #define PG8_WAIT_L(n) asm volatile("s_waitcnt lgkmcnt(" #n ")" ::: "memory")
; #define PG8_BAR __builtin_amdgcn_s_barrier()
; #define PG8_SCHED __builtin_amdgcn_sched_barrier(0)
; template <class Epi, class Sched, bool ALIGN_EPI = false, bool SP2 = false>
; __device__ __forceinline__ void gemm_phase(LAS unsigned char* lds, const Gemm g, const Sched& S, const Epi& E) {
;     ...
;             PG8_LDA(At, 1, 1); PG8_STAGE(PG8_SB(1, 0), b3, voffB); PG8_STAGE(PG8_SB(1, 1), b3 + hstep, voffB); PG8_STAGE(PG8_SA(1, 0), a3, voffA);
;             PG8_WAIT_V(8); PG8_WAIT_L(0); PG8_BAR; PG8_MMA(1, 0, At, B0); PG8_MMA(1, 1, At, B1); PG8_BAR; PG8_SCHED;
;     ...
;         if constexpr (ALIGN_EPI) { if (wr == 0) PG8_BAR; }
	s_setprio 0
	s_add_i32 s28, s45, s9
	v_lshl_add_u64 v[140:141], v[140:141], 0, s[12:13]
	s_mov_b32 m0, s28
	ds_read_b128 v[182:185], v149 offset:49152
	ds_read_b128 v[194:197], v149 offset:50176
	ds_read_b128 v[198:201], v149 offset:51200
	ds_read_b128 v[202:205], v149 offset:52224
	ds_read_b128 v[206:209], v149 offset:53248
	ds_read_b128 v[210:213], v149 offset:54272
	ds_read_b128 v[214:217], v149 offset:55296
	ds_read_b128 v[218:221], v149 offset:56320
	global_load_lds_dwordx4 v[140:141], off
	s_add_i32 m0, s28, 0x2000
	s_add_u32 s26, s26, 0x80080
	v_lshl_add_u64 v[140:141], v[186:187], 0, s[12:13]
	s_addc_u32 s27, s27, 0
	s_add_i32 s28, s47, s9
	global_load_lds_dwordx4 v[140:141], off
	v_lshl_add_u64 v[140:141], s[26:27], 0, v[0:1]
	s_mov_b32 m0, s28
	s_nop 0
	global_load_lds_dwordx4 v[140:141], off
	v_lshl_add_u64 v[140:141], s[26:27], 0, v[130:131]
	s_add_i32 m0, s28, 0x2000
	s_nop 0
	global_load_lds_dwordx4 v[140:141], off
	v_lshl_add_u64 v[140:141], v[188:189], 0, s[12:13]
	s_mov_b32 m0, s40
	s_nop 0
	global_load_lds_dwordx4 v[140:141], off
	v_lshl_add_u64 v[140:141], v[190:191], 0, s[12:13]
	s_mov_b32 m0, s41
	s_nop 0
	global_load_lds_dwordx4 v[140:141], off
	s_waitcnt vmcnt(8)
	s_waitcnt lgkmcnt(0)
	s_setprio 1
	s_barrier
	v_mfma_f32_16x16x32_bf16 v[62:65], v[150:153], v[182:185], v[62:65]
	v_mfma_f32_16x16x32_bf16 v[62:65], v[154:157], v[194:197], v[62:65]
	v_mfma_f32_16x16x32_bf16 v[58:61], v[158:161], v[182:185], v[58:61]
	v_mfma_f32_16x16x32_bf16 v[58:61], v[162:165], v[194:197], v[58:61]
	v_mfma_f32_16x16x32_bf16 v[42:45], v[158:161], v[198:201], v[42:45]
	v_mfma_f32_16x16x32_bf16 v[42:45], v[162:165], v[202:205], v[42:45]
	v_mfma_f32_16x16x32_bf16 v[46:49], v[150:153], v[198:201], v[46:49]
	v_mfma_f32_16x16x32_bf16 v[46:49], v[154:157], v[202:205], v[46:49]
	v_mfma_f32_16x16x32_bf16 v[30:33], v[150:153], v[206:209], v[30:33]
	v_mfma_f32_16x16x32_bf16 v[30:33], v[154:157], v[210:213], v[30:33]
	v_mfma_f32_16x16x32_bf16 v[26:29], v[158:161], v[206:209], v[26:29]
	v_mfma_f32_16x16x32_bf16 v[26:29], v[162:165], v[210:213], v[26:29]
	v_mfma_f32_16x16x32_bf16 v[10:13], v[158:161], v[214:217], v[10:13]
	v_mfma_f32_16x16x32_bf16 v[10:13], v[162:165], v[218:221], v[10:13]
	v_mfma_f32_16x16x32_bf16 v[14:17], v[150:153], v[214:217], v[14:17]
	v_mfma_f32_16x16x32_bf16 v[14:17], v[154:157], v[218:221], v[14:17]
	v_mfma_f32_16x16x32_bf16 v[54:57], v[166:169], v[182:185], v[54:57]
	v_mfma_f32_16x16x32_bf16 v[54:57], v[170:173], v[194:197], v[54:57]
	v_mfma_f32_16x16x32_bf16 v[50:53], v[174:177], v[182:185], v[50:53]
	v_mfma_f32_16x16x32_bf16 v[50:53], v[178:181], v[194:197], v[50:53]
	v_mfma_f32_16x16x32_bf16 v[34:37], v[174:177], v[198:201], v[34:37]
	v_mfma_f32_16x16x32_bf16 v[34:37], v[178:181], v[202:205], v[34:37]
	v_mfma_f32_16x16x32_bf16 v[38:41], v[166:169], v[198:201], v[38:41]
	v_mfma_f32_16x16x32_bf16 v[38:41], v[170:173], v[202:205], v[38:41]
	v_mfma_f32_16x16x32_bf16 v[22:25], v[166:169], v[206:209], v[22:25]
	v_mfma_f32_16x16x32_bf16 v[22:25], v[170:173], v[210:213], v[22:25]
	v_mfma_f32_16x16x32_bf16 v[18:21], v[174:177], v[206:209], v[18:21]
	v_mfma_f32_16x16x32_bf16 v[18:21], v[178:181], v[210:213], v[18:21]
	v_mfma_f32_16x16x32_bf16 v[2:5], v[174:177], v[214:217], v[2:5]
	v_mfma_f32_16x16x32_bf16 v[2:5], v[178:181], v[218:221], v[2:5]
	v_mfma_f32_16x16x32_bf16 v[6:9], v[166:169], v[214:217], v[6:9]
	v_mfma_f32_16x16x32_bf16 v[6:9], v[170:173], v[218:221], v[6:9]
	s_barrier
	s_setprio 0
	s_add_i32 s44, s44, 2
	s_add_u32 s24, s24, 0x100
	s_addc_u32 s25, s25, 0
	s_add_u32 s35, s35, 0x100
	s_addc_u32 s43, s43, 0
	s_cmp_gt_u32 s44, 29
	s_cbranch_scc0 .LBB0_173
	s_and_b64 vcc, exec, s[4:5]
	s_cbranch_vccz .LBB0_176
	s_barrier
	s_setprio 1

; #define PG8_STAGE(bufoff, gbase, voff) do { _Pragma("unroll") for (int _i = 0; _i < 2; ++_i) \
;         __builtin_amdgcn_global_load_lds((const unsigned*)((const char*)(gbase) + (voff)[_i]), (LAS unsigned*)(lds + (bufoff) + ldsw + _i * 8192), 16, 0, 0); } while (0)
; #define PG8_LDA(dst, b, h) do { _Pragma("unroll") for (int m = 0; m < 4; ++m) _Pragma("unroll") for (int k = 0; k < 2; ++k) dst[m][k] = *(const LAS bf16x8*)(lds + PG8_SA(b, h) + aoff + m * 2048 + k * 1024); } while (0)
; #define PG8_LDB(dst, b, h) do { _Pragma("unroll") for (int n = 0; n < 2; ++n) _Pragma("unroll") for (int k = 0; k < 2; ++k) dst[n][k] = *(const LAS bf16x8*)(lds + PG8_SB(b, h) + boff + n * 2048 + k * 1024); } while (0)
; #define PG8_MMA(ai, bj, At, Bt) do { __builtin_amdgcn_s_setprio(1); _Pragma("unroll") for (int m = 0; m < 4; ++m) _Pragma("unroll") for (int n = 0; n < 2; ++n) _Pragma("unroll") for (int k = 0; k < 2; ++k) \
;         acc[ai][bj][m][n] = __builtin_amdgcn_mfma_f32_16x16x32_bf16(Bt[n][k], At[m][k], acc[ai][bj][m][n], 0, 0, 0); __builtin_amdgcn_s_setprio(0); } while (0)
; template <class Epi, class Sched, bool ALIGN_EPI = false, bool SP2 = false>
; __device__ __forceinline__ void gemm_phase(LAS unsigned char* lds, const Gemm g, const Sched& S, const Epi& E) {
;     ...
;         const char* nA = has_next ? (const char*)g.A + (size_t)nxt.pm * tstep : cA; const char* nB = has_next ? (const char*)g.Bt + (size_t)nxt.pn * tstep : cB;
;         for (int t = 0; t < nt; t += 2) {
;             const bool last = (t == nt - 2);
;             const char* a1 = cA + (size_t)(t + 1) * kstep;
;             const char* a2 = last ? nA : cA + (size_t)(t + 2) * kstep; const char* b2 = last ? nB : cB + (size_t)(t + 2) * kstep;
;             const char* a3 = a2 + kstep; const char* b3 = b2 + kstep;
;             if (last && has_next) S.a_ready(nxt);
;             if constexpr (SP2) {
;             PG8_LDB(B0, 0, 0); PG8_LDB(B1, 0, 1); PG8_SCHED; PG8_LDA(At, 0, 0); PG8_STAGE(PG8_SA(1, 1), a1 + hstep, voffA);
;             PG8_WAIT_V(8); PG8_WAIT_L(0); PG8_BAR; PG8_MMA(0, 0, At, B0); PG8_MMA(0, 1, At, B1); PG8_BAR; PG8_SCHED;
;             PG8_LDA(At, 0, 1); PG8_STAGE(PG8_SB(0, 0), b2, voffB); PG8_STAGE(PG8_SB(0, 1), b2 + hstep, voffB); PG8_STAGE(PG8_SA(0, 0), a2, voffA);
;             PG8_WAIT_V(8); PG8_WAIT_L(0); PG8_BAR; PG8_MMA(1, 0, At, B0); PG8_MMA(1, 1, At, B1); PG8_BAR; PG8_SCHED;
.LBB0_257:
	s_add_u32 s24, s22, 0x100
	s_addc_u32 s25, s23, 0
	s_add_i32 s50, 0, 0x10000
	s_cmpk_eq_i32 s49, 0x54
	s_cselect_b32 s29, s1, s25
	s_cselect_b32 s28, s0, s24
	s_cselect_b32 s27, s21, s48
	s_cselect_b32 s26, s20, s47
	s_add_i32 s51, 0, 0x14000
	v_add_u32_e32 v126, s50, v247
	v_add_u32_e32 v158, s51, v247
	ds_read_b128 v[90:93], v126
	ds_read_b128 v[102:105], v126 offset:1024
	ds_read_b128 v[114:117], v126 offset:2048
	ds_read_b128 v[126:129], v126 offset:3072
	ds_read_b128 v[138:141], v158
	ds_read_b128 v[142:145], v158 offset:1024
	ds_read_b128 v[154:157], v158 offset:2048
	ds_read_b128 v[158:161], v158 offset:3072
	v_lshl_add_u64 v[186:187], s[22:23], 0, v[200:201]
	s_add_i32 m0, s6, 0xc000
	ds_read_b128 v[162:165], v249
	ds_read_b128 v[166:169], v249 offset:1024
	ds_read_b128 v[170:173], v249 offset:2048
	ds_read_b128 v[174:177], v249 offset:3072
	ds_read_b128 v[178:181], v249 offset:4096
	ds_read_b128 v[182:185], v249 offset:5120
	ds_read_b128 v[204:207], v249 offset:6144
	ds_read_b128 v[208:211], v249 offset:7168
	global_load_lds_dwordx4 v[186:187], off
	v_lshl_add_u64 v[186:187], s[22:23], 0, v[202:203]
	s_add_i32 m0, s6, 0xe000
	s_nop 0
	global_load_lds_dwordx4 v[186:187], off
	s_waitcnt vmcnt(8)
	s_waitcnt lgkmcnt(0)
	s_setprio 1
	s_barrier
	v_mfma_f32_16x16x32_bf16 v[150:153], v[90:93], v[162:165], v[150:153]
	v_mfma_f32_16x16x32_bf16 v[150:153], v[102:105], v[166:169], v[150:153]
	v_mfma_f32_16x16x32_bf16 v[146:149], v[114:117], v[162:165], v[146:149]
	v_mfma_f32_16x16x32_bf16 v[146:149], v[126:129], v[166:169], v[146:149]
	v_mfma_f32_16x16x32_bf16 v[118:121], v[114:117], v[170:173], v[118:121]
	v_mfma_f32_16x16x32_bf16 v[118:121], v[126:129], v[174:177], v[118:121]
	v_mfma_f32_16x16x32_bf16 v[122:125], v[90:93], v[170:173], v[122:125]
	v_mfma_f32_16x16x32_bf16 v[122:125], v[102:105], v[174:177], v[122:125]
	v_mfma_f32_16x16x32_bf16 v[98:101], v[90:93], v[178:181], v[98:101]
	v_mfma_f32_16x16x32_bf16 v[98:101], v[102:105], v[182:185], v[98:101]
	v_mfma_f32_16x16x32_bf16 v[94:97], v[114:117], v[178:181], v[94:97]
	v_mfma_f32_16x16x32_bf16 v[94:97], v[126:129], v[182:185], v[94:97]
	v_mfma_f32_16x16x32_bf16 v[74:77], v[114:117], v[204:207], v[74:77]
	v_mfma_f32_16x16x32_bf16 v[74:77], v[126:129], v[208:211], v[74:77]
	v_mfma_f32_16x16x32_bf16 v[78:81], v[90:93], v[204:207], v[78:81]
	v_mfma_f32_16x16x32_bf16 v[78:81], v[102:105], v[208:211], v[78:81]
	v_mfma_f32_16x16x32_bf16 v[134:137], v[138:141], v[162:165], v[134:137]
	v_mfma_f32_16x16x32_bf16 v[134:137], v[142:145], v[166:169], v[134:137]
	v_mfma_f32_16x16x32_bf16 v[130:133], v[154:157], v[162:165], v[130:133]
	v_mfma_f32_16x16x32_bf16 v[130:133], v[158:161], v[166:169], v[130:133]
	v_mfma_f32_16x16x32_bf16 v[106:109], v[154:157], v[170:173], v[106:109]
	v_mfma_f32_16x16x32_bf16 v[106:109], v[158:161], v[174:177], v[106:109]
	v_mfma_f32_16x16x32_bf16 v[110:113], v[138:141], v[170:173], v[110:113]
	v_mfma_f32_16x16x32_bf16 v[110:113], v[142:145], v[174:177], v[110:113]
	v_mfma_f32_16x16x32_bf16 v[86:89], v[138:141], v[178:181], v[86:89]
	v_mfma_f32_16x16x32_bf16 v[86:89], v[142:145], v[182:185], v[86:89]
	v_mfma_f32_16x16x32_bf16 v[82:85], v[154:157], v[178:181], v[82:85]
	v_mfma_f32_16x16x32_bf16 v[82:85], v[158:161], v[182:185], v[82:85]
	v_mfma_f32_16x16x32_bf16 v[66:69], v[154:157], v[204:207], v[66:69]
	v_mfma_f32_16x16x32_bf16 v[66:69], v[158:161], v[208:211], v[66:69]
	v_mfma_f32_16x16x32_bf16 v[70:73], v[138:141], v[204:207], v[70:73]
	v_mfma_f32_16x16x32_bf16 v[70:73], v[142:145], v[208:211], v[70:73]
	s_barrier
	s_setprio 0
	s_add_i32 s22, s50, s2
	v_lshl_add_u64 v[186:187], s[26:27], 0, v[0:1]
	s_mov_b32 m0, s22
	ds_read_b128 v[162:165], v249 offset:16384
	ds_read_b128 v[166:169], v249 offset:17408
	ds_read_b128 v[170:173], v249 offset:18432
	ds_read_b128 v[174:177], v249 offset:19456
	ds_read_b128 v[178:181], v249 offset:20480
	ds_read_b128 v[182:185], v249 offset:21504
	ds_read_b128 v[204:207], v249 offset:22528
	ds_read_b128 v[208:211], v249 offset:23552
	global_load_lds_dwordx4 v[186:187], off
	s_add_i32 m0, s22, 0x2000
	s_add_u32 s22, s26, 0x160000
	v_lshl_add_u64 v[188:189], s[26:27], 0, v[194:195]
	s_addc_u32 s23, s27, 0
	s_add_i32 s50, s51, s2
	global_load_lds_dwordx4 v[188:189], off
	v_lshl_add_u64 v[190:191], s[22:23], 0, v[0:1]
	s_mov_b32 m0, s50
	v_lshl_add_u64 v[192:193], s[28:29], 0, v[196:197]
	global_load_lds_dwordx4 v[190:191], off
	v_lshl_add_u64 v[190:191], s[22:23], 0, v[194:195]
	s_add_i32 m0, s50, 0x2000
	s_nop 0
	global_load_lds_dwordx4 v[190:191], off
	v_lshl_add_u64 v[190:191], s[28:29], 0, v[198:199]
	s_mov_b32 m0, s6
	s_nop 0
	global_load_lds_dwordx4 v[190:191], off
	s_mov_b32 m0, s7
	s_nop 0
	global_load_lds_dwordx4 v[192:193], off
	s_waitcnt vmcnt(8)
	s_waitcnt lgkmcnt(0)
	s_setprio 1
	s_barrier
; #define PG8_STAGE(bufoff, gbase, voff) do { _Pragma("unroll") for (int _i = 0; _i < 2; ++_i) \
;         __builtin_amdgcn_global_load_lds((const unsigned*)((const char*)(gbase) + (voff)[_i]), (LAS unsigned*)(lds + (bufoff) + ldsw + _i * 8192), 16, 0, 0); } while (0)
; #define PG8_LDA(dst, b, h) do { _Pragma("unroll") for (int m = 0; m < 4; ++m) _Pragma("unroll") for (int k = 0; k < 2; ++k) dst[m][k] = *(const LAS bf16x8*)(lds + PG8_SA(b, h) + aoff + m * 2048 + k * 1024); } while (0)
; #define PG8_LDB(dst, b, h) do { _Pragma("unroll") for (int n = 0; n < 2; ++n) _Pragma("unroll") for (int k = 0; k < 2; ++k) dst[n][k] = *(const LAS bf16x8*)(lds + PG8_SB(b, h) + boff + n * 2048 + k * 1024); } while (0)
; #define PG8_MMA(ai, bj, At, Bt) do { __builtin_amdgcn_s_setprio(1); _Pragma("unroll") for (int m = 0; m < 4; ++m) _Pragma("unroll") for (int n = 0; n < 2; ++n) _Pragma("unroll") for (int k = 0; k < 2; ++k) \
;         acc[ai][bj][m][n] = __builtin_amdgcn_mfma_f32_16x16x32_bf16(Bt[n][k], At[m][k], acc[ai][bj][m][n], 0, 0, 0); __builtin_amdgcn_s_setprio(0); } while (0)
; #define PG8_WAIT_V(n) asm volatile("s_waitcnt vmcnt(" #n ")" ::: "memory")
; #define PG8_WAIT_L(n) asm volatile("s_waitcnt lgkmcnt(" #n ")" ::: "memory")
; #define PG8_BAR __builtin_amdgcn_s_barrier()
; #define PG8_SCHED __builtin_amdgcn_sched_barrier(0)
; template <class Epi, class Sched, bool ALIGN_EPI = false, bool SP2 = false>
; __device__ __forceinline__ void gemm_phase(LAS unsigned char* lds, const Gemm g, const Sched& S, const Epi& E) {
;     ...
;             PG8_WAIT_V(8); PG8_WAIT_L(0); PG8_BAR; PG8_MMA(1, 0, At, B0); PG8_MMA(1, 1, At, B1); PG8_BAR; PG8_SCHED;
;             PG8_LDB(B0, 1, 0); PG8_LDB(B1, 1, 1); PG8_SCHED; PG8_LDA(At, 1, 0); PG8_STAGE(PG8_SA(0, 1), a2 + hstep, voffA);
;             PG8_WAIT_V(8); PG8_WAIT_L(0); PG8_BAR; PG8_MMA(0, 0, At, B0); PG8_MMA(0, 1, At, B1); PG8_BAR; PG8_SCHED;
	v_mfma_f32_16x16x32_bf16 v[62:65], v[90:93], v[162:165], v[62:65]
	v_mfma_f32_16x16x32_bf16 v[62:65], v[102:105], v[166:169], v[62:65]
	v_mfma_f32_16x16x32_bf16 v[58:61], v[114:117], v[162:165], v[58:61]
	v_mfma_f32_16x16x32_bf16 v[58:61], v[126:129], v[166:169], v[58:61]
	v_mfma_f32_16x16x32_bf16 v[42:45], v[114:117], v[170:173], v[42:45]
	v_mfma_f32_16x16x32_bf16 v[42:45], v[126:129], v[174:177], v[42:45]
	v_mfma_f32_16x16x32_bf16 v[46:49], v[90:93], v[170:173], v[46:49]
	v_mfma_f32_16x16x32_bf16 v[46:49], v[102:105], v[174:177], v[46:49]
	v_mfma_f32_16x16x32_bf16 v[30:33], v[90:93], v[178:181], v[30:33]
	v_mfma_f32_16x16x32_bf16 v[30:33], v[102:105], v[182:185], v[30:33]
	v_mfma_f32_16x16x32_bf16 v[26:29], v[114:117], v[178:181], v[26:29]
	v_mfma_f32_16x16x32_bf16 v[26:29], v[126:129], v[182:185], v[26:29]
	v_mfma_f32_16x16x32_bf16 v[10:13], v[114:117], v[204:207], v[10:13]
	v_mfma_f32_16x16x32_bf16 v[10:13], v[126:129], v[208:211], v[10:13]
	v_mfma_f32_16x16x32_bf16 v[14:17], v[90:93], v[204:207], v[14:17]
	v_mfma_f32_16x16x32_bf16 v[14:17], v[102:105], v[208:211], v[14:17]
	v_mfma_f32_16x16x32_bf16 v[54:57], v[138:141], v[162:165], v[54:57]
	v_mfma_f32_16x16x32_bf16 v[54:57], v[142:145], v[166:169], v[54:57]
	v_mfma_f32_16x16x32_bf16 v[50:53], v[154:157], v[162:165], v[50:53]
	v_mfma_f32_16x16x32_bf16 v[50:53], v[158:161], v[166:169], v[50:53]
	v_mfma_f32_16x16x32_bf16 v[34:37], v[154:157], v[170:173], v[34:37]
	v_mfma_f32_16x16x32_bf16 v[34:37], v[158:161], v[174:177], v[34:37]
	v_mfma_f32_16x16x32_bf16 v[38:41], v[138:141], v[170:173], v[38:41]
	v_mfma_f32_16x16x32_bf16 v[38:41], v[142:145], v[174:177], v[38:41]
	v_mfma_f32_16x16x32_bf16 v[22:25], v[138:141], v[178:181], v[22:25]
	v_mfma_f32_16x16x32_bf16 v[22:25], v[142:145], v[182:185], v[22:25]
	v_mfma_f32_16x16x32_bf16 v[18:21], v[154:157], v[178:181], v[18:21]
	v_mfma_f32_16x16x32_bf16 v[18:21], v[158:161], v[182:185], v[18:21]
	v_mfma_f32_16x16x32_bf16 v[2:5], v[154:157], v[204:207], v[2:5]
	v_mfma_f32_16x16x32_bf16 v[2:5], v[158:161], v[208:211], v[2:5]
	v_mfma_f32_16x16x32_bf16 v[6:9], v[138:141], v[204:207], v[6:9]
	v_mfma_f32_16x16x32_bf16 v[6:9], v[142:145], v[208:211], v[6:9]
	s_barrier
	s_setprio 0
	s_add_i32 s50, 0, 0x18000
	s_add_i32 s51, 0, 0x1c000
	v_add_u32_e32 v126, s50, v247
	v_add_u32_e32 v158, s51, v247
	ds_read_b128 v[90:93], v126
	ds_read_b128 v[102:105], v126 offset:1024
	ds_read_b128 v[114:117], v126 offset:2048
	ds_read_b128 v[126:129], v126 offset:3072
	ds_read_b128 v[138:141], v158
	ds_read_b128 v[142:145], v158 offset:1024
	ds_read_b128 v[154:157], v158 offset:2048
	ds_read_b128 v[158:161], v158 offset:3072
	s_add_u32 s22, s28, 0x160000
	s_addc_u32 s23, s29, 0
	s_mov_b32 m0, s8
	v_lshl_add_u64 v[212:213], s[22:23], 0, v[198:199]
	ds_read_b128 v[162:165], v249 offset:32768
	ds_read_b128 v[166:169], v249 offset:33792
	ds_read_b128 v[170:173], v249 offset:34816
	ds_read_b128 v[174:177], v249 offset:35840
	ds_read_b128 v[178:181], v249 offset:36864
	ds_read_b128 v[182:185], v249 offset:37888
	ds_read_b128 v[204:207], v249 offset:38912
	ds_read_b128 v[208:211], v249 offset:39936
	global_load_lds_dwordx4 v[212:213], off
	v_lshl_add_u64 v[212:213], s[22:23], 0, v[196:197]
	s_mov_b32 m0, s31
	s_nop 0
	global_load_lds_dwordx4 v[212:213], off
	s_waitcnt vmcnt(8)
	s_waitcnt lgkmcnt(0)
	s_setprio 1
	s_barrier
	v_mfma_f32_16x16x32_bf16 v[150:153], v[90:93], v[162:165], v[150:153]
	v_mfma_f32_16x16x32_bf16 v[150:153], v[102:105], v[166:169], v[150:153]
	v_mfma_f32_16x16x32_bf16 v[146:149], v[114:117], v[162:165], v[146:149]
	v_mfma_f32_16x16x32_bf16 v[146:149], v[126:129], v[166:169], v[146:149]
	v_mfma_f32_16x16x32_bf16 v[118:121], v[114:117], v[170:173], v[118:121]
	v_mfma_f32_16x16x32_bf16 v[118:121], v[126:129], v[174:177], v[118:121]
	v_mfma_f32_16x16x32_bf16 v[122:125], v[90:93], v[170:173], v[122:125]
	v_mfma_f32_16x16x32_bf16 v[122:125], v[102:105], v[174:177], v[122:125]
	v_mfma_f32_16x16x32_bf16 v[98:101], v[90:93], v[178:181], v[98:101]
	v_mfma_f32_16x16x32_bf16 v[98:101], v[102:105], v[182:185], v[98:101]
	v_mfma_f32_16x16x32_bf16 v[94:97], v[114:117], v[178:181], v[94:97]
	v_mfma_f32_16x16x32_bf16 v[94:97], v[126:129], v[182:185], v[94:97]
	v_mfma_f32_16x16x32_bf16 v[74:77], v[114:117], v[204:207], v[74:77]
	v_mfma_f32_16x16x32_bf16 v[74:77], v[126:129], v[208:211], v[74:77]
	v_mfma_f32_16x16x32_bf16 v[78:81], v[90:93], v[204:207], v[78:81]
	v_mfma_f32_16x16x32_bf16 v[78:81], v[102:105], v[208:211], v[78:81]
	v_mfma_f32_16x16x32_bf16 v[134:137], v[138:141], v[162:165], v[134:137]
	v_mfma_f32_16x16x32_bf16 v[134:137], v[142:145], v[166:169], v[134:137]
	v_mfma_f32_16x16x32_bf16 v[130:133], v[154:157], v[162:165], v[130:133]
	v_mfma_f32_16x16x32_bf16 v[130:133], v[158:161], v[166:169], v[130:133]
	v_mfma_f32_16x16x32_bf16 v[106:109], v[154:157], v[170:173], v[106:109]
	v_mfma_f32_16x16x32_bf16 v[106:109], v[158:161], v[174:177], v[106:109]
	v_mfma_f32_16x16x32_bf16 v[110:113], v[138:141], v[170:173], v[110:113]
	v_mfma_f32_16x16x32_bf16 v[110:113], v[142:145], v[174:177], v[110:113]
	v_mfma_f32_16x16x32_bf16 v[86:89], v[138:141], v[178:181], v[86:89]
	v_mfma_f32_16x16x32_bf16 v[86:89], v[142:145], v[182:185], v[86:89]
	v_mfma_f32_16x16x32_bf16 v[82:85], v[154:157], v[178:181], v[82:85]
	v_mfma_f32_16x16x32_bf16 v[82:85], v[158:161], v[182:185], v[82:85]
	v_mfma_f32_16x16x32_bf16 v[66:69], v[154:157], v[204:207], v[66:69]
	v_mfma_f32_16x16x32_bf16 v[66:69], v[158:161], v[208:211], v[66:69]
	v_mfma_f32_16x16x32_bf16 v[70:73], v[138:141], v[204:207], v[70:73]
	v_mfma_f32_16x16x32_bf16 v[70:73], v[142:145], v[208:211], v[70:73]
	s_barrier
; #define PG8_STAGE(bufoff, gbase, voff) do { _Pragma("unroll") for (int _i = 0; _i < 2; ++_i) \
;         __builtin_amdgcn_global_load_lds((const unsigned*)((const char*)(gbase) + (voff)[_i]), (LAS unsigned*)(lds + (bufoff) + ldsw + _i * 8192), 16, 0, 0); } while (0)
; #define PG8_LDA(dst, b, h) do { _Pragma("unroll") for (int m = 0; m < 4; ++m) _Pragma("unroll") for (int k = 0; k < 2; ++k) dst[m][k] = *(const LAS bf16x8*)(lds + PG8_SA(b, h) + aoff + m * 2048 + k * 1024); } while (0)
; #define PG8_MMA(ai, bj, At, Bt) do { __builtin_amdgcn_s_setprio(1); _Pragma("unroll") for (int m = 0; m < 4; ++m) _Pragma("unroll") for (int n = 0; n < 2; ++n) _Pragma("unroll") for (int k = 0; k < 2; ++k) \
;         acc[ai][bj][m][n] = __builtin_amdgcn_mfma_f32_16x16x32_bf16(Bt[n][k], At[m][k], acc[ai][bj][m][n], 0, 0, 0); __builtin_amdgcn_s_setprio(0); } while (0)
; #define PG8_WAIT_V(n) asm volatile("s_waitcnt vmcnt(" #n ")" ::: "memory")
; #define PG8_WAIT_L(n) asm volatile("s_waitcnt lgkmcnt(" #n ")" ::: "memory")
; #define PG8_BAR __builtin_amdgcn_s_barrier()
; #define PG8_SCHED __builtin_amdgcn_sched_barrier(0)
; template <class Epi, class Sched, bool ALIGN_EPI = false, bool SP2 = false>
; __device__ __forceinline__ void gemm_phase(LAS unsigned char* lds, const Gemm g, const Sched& S, const Epi& E) {
;     ...
;             PG8_LDA(At, 1, 1); PG8_STAGE(PG8_SB(1, 0), b3, voffB); PG8_STAGE(PG8_SB(1, 1), b3 + hstep, voffB); PG8_STAGE(PG8_SA(1, 0), a3, voffA);
;             PG8_WAIT_V(8); PG8_WAIT_L(0); PG8_BAR; PG8_MMA(1, 0, At, B0); PG8_MMA(1, 1, At, B1); PG8_BAR; PG8_SCHED;
;     ...
;         if constexpr (ALIGN_EPI) { if (wr == 0) PG8_BAR; }
	s_setprio 0
	s_add_i32 s22, s50, s2
	v_lshl_add_u64 v[186:187], v[186:187], 0, s[12:13]
	s_mov_b32 m0, s22
	ds_read_b128 v[162:165], v249 offset:49152
	ds_read_b128 v[166:169], v249 offset:50176
	ds_read_b128 v[170:173], v249 offset:51200
	ds_read_b128 v[174:177], v249 offset:52224
	ds_read_b128 v[178:181], v249 offset:53248
	ds_read_b128 v[182:185], v249 offset:54272
	ds_read_b128 v[204:207], v249 offset:55296
	ds_read_b128 v[208:211], v249 offset:56320
	global_load_lds_dwordx4 v[186:187], off
	s_add_i32 m0, s22, 0x2000
	s_add_u32 s22, s26, 0x160080
	v_lshl_add_u64 v[186:187], v[188:189], 0, s[12:13]
	s_addc_u32 s23, s27, 0
	s_add_i32 s26, s51, s2
	global_load_lds_dwordx4 v[186:187], off
	v_lshl_add_u64 v[186:187], s[22:23], 0, v[0:1]
	s_mov_b32 m0, s26
	s_nop 0
	global_load_lds_dwordx4 v[186:187], off
	v_lshl_add_u64 v[186:187], s[22:23], 0, v[194:195]
	s_add_i32 m0, s26, 0x2000
	s_nop 0
	global_load_lds_dwordx4 v[186:187], off
	v_lshl_add_u64 v[186:187], v[190:191], 0, s[12:13]
	s_mov_b32 m0, s35
	s_nop 0
	global_load_lds_dwordx4 v[186:187], off
	v_lshl_add_u64 v[186:187], v[192:193], 0, s[12:13]
	s_mov_b32 m0, s40
	s_nop 0
	global_load_lds_dwordx4 v[186:187], off
	s_waitcnt vmcnt(8)
	s_waitcnt lgkmcnt(0)
	s_setprio 1
	s_barrier
	v_mfma_f32_16x16x32_bf16 v[62:65], v[90:93], v[162:165], v[62:65]
	v_mfma_f32_16x16x32_bf16 v[62:65], v[102:105], v[166:169], v[62:65]
	v_mfma_f32_16x16x32_bf16 v[58:61], v[114:117], v[162:165], v[58:61]
	v_mfma_f32_16x16x32_bf16 v[58:61], v[126:129], v[166:169], v[58:61]
	v_mfma_f32_16x16x32_bf16 v[42:45], v[114:117], v[170:173], v[42:45]
	v_mfma_f32_16x16x32_bf16 v[42:45], v[126:129], v[174:177], v[42:45]
	v_mfma_f32_16x16x32_bf16 v[46:49], v[90:93], v[170:173], v[46:49]
	v_mfma_f32_16x16x32_bf16 v[46:49], v[102:105], v[174:177], v[46:49]
	v_mfma_f32_16x16x32_bf16 v[30:33], v[90:93], v[178:181], v[30:33]
	v_mfma_f32_16x16x32_bf16 v[30:33], v[102:105], v[182:185], v[30:33]
	v_mfma_f32_16x16x32_bf16 v[26:29], v[114:117], v[178:181], v[26:29]
	v_mfma_f32_16x16x32_bf16 v[26:29], v[126:129], v[182:185], v[26:29]
	v_mfma_f32_16x16x32_bf16 v[10:13], v[114:117], v[204:207], v[10:13]
	v_mfma_f32_16x16x32_bf16 v[10:13], v[126:129], v[208:211], v[10:13]
	v_mfma_f32_16x16x32_bf16 v[14:17], v[90:93], v[204:207], v[14:17]
	v_mfma_f32_16x16x32_bf16 v[14:17], v[102:105], v[208:211], v[14:17]
	v_mfma_f32_16x16x32_bf16 v[54:57], v[138:141], v[162:165], v[54:57]
	v_mfma_f32_16x16x32_bf16 v[54:57], v[142:145], v[166:169], v[54:57]
	v_mfma_f32_16x16x32_bf16 v[50:53], v[154:157], v[162:165], v[50:53]
	v_mfma_f32_16x16x32_bf16 v[50:53], v[158:161], v[166:169], v[50:53]
	v_mfma_f32_16x16x32_bf16 v[34:37], v[154:157], v[170:173], v[34:37]
	v_mfma_f32_16x16x32_bf16 v[34:37], v[158:161], v[174:177], v[34:37]
	v_mfma_f32_16x16x32_bf16 v[38:41], v[138:141], v[170:173], v[38:41]
	v_mfma_f32_16x16x32_bf16 v[38:41], v[142:145], v[174:177], v[38:41]
	v_mfma_f32_16x16x32_bf16 v[22:25], v[138:141], v[178:181], v[22:25]
	v_mfma_f32_16x16x32_bf16 v[22:25], v[142:145], v[182:185], v[22:25]
	v_mfma_f32_16x16x32_bf16 v[18:21], v[154:157], v[178:181], v[18:21]
	v_mfma_f32_16x16x32_bf16 v[18:21], v[158:161], v[182:185], v[18:21]
	v_mfma_f32_16x16x32_bf16 v[2:5], v[154:157], v[204:207], v[2:5]
	v_mfma_f32_16x16x32_bf16 v[2:5], v[158:161], v[208:211], v[2:5]
	v_mfma_f32_16x16x32_bf16 v[6:9], v[138:141], v[204:207], v[6:9]
	v_mfma_f32_16x16x32_bf16 v[6:9], v[142:145], v[208:211], v[6:9]
	s_barrier
	s_setprio 0
	s_add_i32 s49, s49, 2
	s_add_u32 s47, s47, 0x100
	s_addc_u32 s48, s48, 0
	s_cmpk_gt_u32 s49, 0x55
	s_mov_b64 s[22:23], s[24:25]
	s_cbranch_scc0 .LBB0_257
	s_and_b64 vcc, exec, s[18:19]
	s_cbranch_vccz .LBB0_260
	s_barrier
	s_setprio 1

; #define PG8_STAGE(bufoff, gbase, voff) do { _Pragma("unroll") for (int _i = 0; _i < 2; ++_i) \
;         __builtin_amdgcn_global_load_lds((const unsigned*)((const char*)(gbase) + (voff)[_i]), (LAS unsigned*)(lds + (bufoff) + ldsw + _i * 8192), 16, 0, 0); } while (0)
; #define PG8_LDA(dst, b, h) do { _Pragma("unroll") for (int m = 0; m < 4; ++m) _Pragma("unroll") for (int k = 0; k < 2; ++k) dst[m][k] = *(const LAS bf16x8*)(lds + PG8_SA(b, h) + aoff + m * 2048 + k * 1024); } while (0)
; #define PG8_LDB(dst, b, h) do { _Pragma("unroll") for (int n = 0; n < 2; ++n) _Pragma("unroll") for (int k = 0; k < 2; ++k) dst[n][k] = *(const LAS bf16x8*)(lds + PG8_SB(b, h) + boff + n * 2048 + k * 1024); } while (0)
; #define PG8_MMA(ai, bj, At, Bt) do { __builtin_amdgcn_s_setprio(1); _Pragma("unroll") for (int m = 0; m < 4; ++m) _Pragma("unroll") for (int n = 0; n < 2; ++n) _Pragma("unroll") for (int k = 0; k < 2; ++k) \
;         acc[ai][bj][m][n] = __builtin_amdgcn_mfma_f32_16x16x32_bf16(Bt[n][k], At[m][k], acc[ai][bj][m][n], 0, 0, 0); __builtin_amdgcn_s_setprio(0); } while (0)
; template <class Epi, class Sched, bool ALIGN_EPI = false, bool SP2 = false>
; __device__ __forceinline__ void gemm_phase(LAS unsigned char* lds, const Gemm g, const Sched& S, const Epi& E) {
;     ...
;         const char* nA = has_next ? (const char*)g.A + (size_t)nxt.pm * tstep : cA; const char* nB = has_next ? (const char*)g.Bt + (size_t)nxt.pn * tstep : cB;
;         for (int t = 0; t < nt; t += 2) {
;             const bool last = (t == nt - 2);
;             const char* a1 = cA + (size_t)(t + 1) * kstep;
;             const char* a2 = last ? nA : cA + (size_t)(t + 2) * kstep; const char* b2 = last ? nB : cB + (size_t)(t + 2) * kstep;
;             const char* a3 = a2 + kstep; const char* b3 = b2 + kstep;
;             if (last && has_next) S.a_ready(nxt);
;             if constexpr (SP2) {
;             PG8_LDB(B0, 0, 0); PG8_LDB(B1, 0, 1); PG8_SCHED; PG8_LDA(At, 0, 0); PG8_STAGE(PG8_SA(1, 1), a1 + hstep, voffA);
;             PG8_WAIT_V(8); PG8_WAIT_L(0); PG8_BAR; PG8_MMA(0, 0, At, B0); PG8_MMA(0, 1, At, B1); PG8_BAR; PG8_SCHED;
;             PG8_LDA(At, 0, 1); PG8_STAGE(PG8_SB(0, 0), b2, voffB); PG8_STAGE(PG8_SB(0, 1), b2 + hstep, voffB); PG8_STAGE(PG8_SA(0, 0), a2, voffA);
;             PG8_WAIT_V(8); PG8_WAIT_L(0); PG8_BAR; PG8_MMA(1, 0, At, B0); PG8_MMA(1, 1, At, B1); PG8_BAR; PG8_SCHED;
.LBB0_359:
	s_add_u32 s28, s26, 0xfff80080
	s_addc_u32 s29, s27, -1
	s_add_i32 s41, 0, 0x10000
	s_cmp_eq_u32 s40, 28
	s_cselect_b32 s31, s6, s29
	s_cselect_b32 s30, s7, s28
	v_add_u32_e32 v0, s41, v159
	s_cselect_b32 s29, s8, s35
	s_cselect_b32 s28, s19, s21
	s_add_i32 s57, 0, 0x14000
	ds_read_b128 v[142:145], v0
	ds_read_b128 v[146:149], v0 offset:1024
	ds_read_b128 v[150:153], v0 offset:2048
	ds_read_b128 v[154:157], v0 offset:3072
	v_add_u32_e32 v0, s57, v159
	ds_read_b128 v[162:165], v0
	ds_read_b128 v[166:169], v0 offset:1024
	ds_read_b128 v[170:173], v0 offset:2048
	ds_read_b128 v[174:177], v0 offset:3072
	v_lshl_add_u64 v[210:211], s[26:27], 0, v[138:139]
	s_add_i32 m0, s44, 0xc000
	ds_read_b128 v[178:181], v161
	ds_read_b128 v[182:185], v161 offset:1024
	ds_read_b128 v[186:189], v161 offset:2048
	ds_read_b128 v[190:193], v161 offset:3072
	ds_read_b128 v[194:197], v161 offset:4096
	ds_read_b128 v[198:201], v161 offset:5120
	ds_read_b128 v[202:205], v161 offset:6144
	ds_read_b128 v[206:209], v161 offset:7168
	global_load_lds_dwordx4 v[210:211], off
	v_lshl_add_u64 v[210:211], s[26:27], 0, v[140:141]
	s_add_i32 m0, s44, 0xe000
	s_nop 0
	global_load_lds_dwordx4 v[210:211], off
	s_waitcnt vmcnt(8)
	s_waitcnt lgkmcnt(0)
	s_setprio 1
	s_barrier
	v_mfma_f32_16x16x32_bf16 v[126:129], v[142:145], v[178:181], v[126:129]
	v_mfma_f32_16x16x32_bf16 v[126:129], v[146:149], v[182:185], v[126:129]
	v_mfma_f32_16x16x32_bf16 v[122:125], v[150:153], v[178:181], v[122:125]
	v_mfma_f32_16x16x32_bf16 v[122:125], v[154:157], v[182:185], v[122:125]
	v_mfma_f32_16x16x32_bf16 v[106:109], v[150:153], v[186:189], v[106:109]
	v_mfma_f32_16x16x32_bf16 v[106:109], v[154:157], v[190:193], v[106:109]
	v_mfma_f32_16x16x32_bf16 v[110:113], v[142:145], v[186:189], v[110:113]
	v_mfma_f32_16x16x32_bf16 v[110:113], v[146:149], v[190:193], v[110:113]
	v_mfma_f32_16x16x32_bf16 v[94:97], v[142:145], v[194:197], v[94:97]
	v_mfma_f32_16x16x32_bf16 v[94:97], v[146:149], v[198:201], v[94:97]
	v_mfma_f32_16x16x32_bf16 v[90:93], v[150:153], v[194:197], v[90:93]
	v_mfma_f32_16x16x32_bf16 v[90:93], v[154:157], v[198:201], v[90:93]
	v_mfma_f32_16x16x32_bf16 v[74:77], v[150:153], v[202:205], v[74:77]
	v_mfma_f32_16x16x32_bf16 v[74:77], v[154:157], v[206:209], v[74:77]
	v_mfma_f32_16x16x32_bf16 v[78:81], v[142:145], v[202:205], v[78:81]
	v_mfma_f32_16x16x32_bf16 v[78:81], v[146:149], v[206:209], v[78:81]
	v_mfma_f32_16x16x32_bf16 v[118:121], v[162:165], v[178:181], v[118:121]
	v_mfma_f32_16x16x32_bf16 v[118:121], v[166:169], v[182:185], v[118:121]
	v_mfma_f32_16x16x32_bf16 v[114:117], v[170:173], v[178:181], v[114:117]
	v_mfma_f32_16x16x32_bf16 v[114:117], v[174:177], v[182:185], v[114:117]
	v_mfma_f32_16x16x32_bf16 v[98:101], v[170:173], v[186:189], v[98:101]
	v_mfma_f32_16x16x32_bf16 v[98:101], v[174:177], v[190:193], v[98:101]
	v_mfma_f32_16x16x32_bf16 v[102:105], v[162:165], v[186:189], v[102:105]
	v_mfma_f32_16x16x32_bf16 v[102:105], v[166:169], v[190:193], v[102:105]
	v_mfma_f32_16x16x32_bf16 v[86:89], v[162:165], v[194:197], v[86:89]
	v_mfma_f32_16x16x32_bf16 v[86:89], v[166:169], v[198:201], v[86:89]
	v_mfma_f32_16x16x32_bf16 v[82:85], v[170:173], v[194:197], v[82:85]
	v_mfma_f32_16x16x32_bf16 v[82:85], v[174:177], v[198:201], v[82:85]
	v_mfma_f32_16x16x32_bf16 v[66:69], v[170:173], v[202:205], v[66:69]
	v_mfma_f32_16x16x32_bf16 v[66:69], v[174:177], v[206:209], v[66:69]
	v_mfma_f32_16x16x32_bf16 v[70:73], v[162:165], v[202:205], v[70:73]
	v_mfma_f32_16x16x32_bf16 v[70:73], v[166:169], v[206:209], v[70:73]
	s_barrier
	s_setprio 0
	s_add_i32 s41, s41, s9
	v_lshl_add_u64 v[210:211], s[28:29], 0, v[134:135]
	s_mov_b32 m0, s41
	ds_read_b128 v[178:181], v161 offset:16384
	ds_read_b128 v[182:185], v161 offset:17408
	ds_read_b128 v[186:189], v161 offset:18432
	ds_read_b128 v[190:193], v161 offset:19456
	ds_read_b128 v[194:197], v161 offset:20480
	ds_read_b128 v[198:201], v161 offset:21504
	ds_read_b128 v[202:205], v161 offset:22528
	ds_read_b128 v[206:209], v161 offset:23552
	global_load_lds_dwordx4 v[210:211], off
	s_add_i32 m0, s41, 0x2000
	s_add_u32 s58, s28, 0x80000
	v_lshl_add_u64 v[212:213], s[28:29], 0, v[130:131]
	s_addc_u32 s59, s29, 0
	s_add_i32 s41, s57, s9
	global_load_lds_dwordx4 v[212:213], off
	v_lshl_add_u64 v[214:215], s[58:59], 0, v[134:135]
	s_mov_b32 m0, s41
	v_lshl_add_u64 v[216:217], s[30:31], 0, v[132:133]
	global_load_lds_dwordx4 v[214:215], off
	v_lshl_add_u64 v[214:215], s[58:59], 0, v[130:131]
	s_add_i32 m0, s41, 0x2000
	s_nop 0
	global_load_lds_dwordx4 v[214:215], off
	v_lshl_add_u64 v[214:215], s[30:31], 0, v[136:137]
	s_mov_b32 m0, s44
	s_nop 0
	global_load_lds_dwordx4 v[214:215], off
	s_mov_b32 m0, s45
	s_nop 0
	global_load_lds_dwordx4 v[216:217], off
	s_waitcnt vmcnt(8)
	s_waitcnt lgkmcnt(0)
	s_setprio 1
	s_barrier
; #define PG8_STAGE(bufoff, gbase, voff) do { _Pragma("unroll") for (int _i = 0; _i < 2; ++_i) \
;         __builtin_amdgcn_global_load_lds((const unsigned*)((const char*)(gbase) + (voff)[_i]), (LAS unsigned*)(lds + (bufoff) + ldsw + _i * 8192), 16, 0, 0); } while (0)
; #define PG8_LDA(dst, b, h) do { _Pragma("unroll") for (int m = 0; m < 4; ++m) _Pragma("unroll") for (int k = 0; k < 2; ++k) dst[m][k] = *(const LAS bf16x8*)(lds + PG8_SA(b, h) + aoff + m * 2048 + k * 1024); } while (0)
; #define PG8_LDB(dst, b, h) do { _Pragma("unroll") for (int n = 0; n < 2; ++n) _Pragma("unroll") for (int k = 0; k < 2; ++k) dst[n][k] = *(const LAS bf16x8*)(lds + PG8_SB(b, h) + boff + n * 2048 + k * 1024); } while (0)
; #define PG8_MMA(ai, bj, At, Bt) do { __builtin_amdgcn_s_setprio(1); _Pragma("unroll") for (int m = 0; m < 4; ++m) _Pragma("unroll") for (int n = 0; n < 2; ++n) _Pragma("unroll") for (int k = 0; k < 2; ++k) \
;         acc[ai][bj][m][n] = __builtin_amdgcn_mfma_f32_16x16x32_bf16(Bt[n][k], At[m][k], acc[ai][bj][m][n], 0, 0, 0); __builtin_amdgcn_s_setprio(0); } while (0)
; #define PG8_WAIT_V(n) asm volatile("s_waitcnt vmcnt(" #n ")" ::: "memory")
; #define PG8_WAIT_L(n) asm volatile("s_waitcnt lgkmcnt(" #n ")" ::: "memory")
; #define PG8_BAR __builtin_amdgcn_s_barrier()
; #define PG8_SCHED __builtin_amdgcn_sched_barrier(0)
; template <class Epi, class Sched, bool ALIGN_EPI = false, bool SP2 = false>
; __device__ __forceinline__ void gemm_phase(LAS unsigned char* lds, const Gemm g, const Sched& S, const Epi& E) {
;     ...
;             PG8_WAIT_V(8); PG8_WAIT_L(0); PG8_BAR; PG8_MMA(1, 0, At, B0); PG8_MMA(1, 1, At, B1); PG8_BAR; PG8_SCHED;
;             PG8_LDB(B0, 1, 0); PG8_LDB(B1, 1, 1); PG8_SCHED; PG8_LDA(At, 1, 0); PG8_STAGE(PG8_SA(0, 1), a2 + hstep, voffA);
;             PG8_WAIT_V(8); PG8_WAIT_L(0); PG8_BAR; PG8_MMA(0, 0, At, B0); PG8_MMA(0, 1, At, B1); PG8_BAR; PG8_SCHED;
	v_mfma_f32_16x16x32_bf16 v[62:65], v[142:145], v[178:181], v[62:65]
	v_mfma_f32_16x16x32_bf16 v[62:65], v[146:149], v[182:185], v[62:65]
	v_mfma_f32_16x16x32_bf16 v[58:61], v[150:153], v[178:181], v[58:61]
	v_mfma_f32_16x16x32_bf16 v[58:61], v[154:157], v[182:185], v[58:61]
	v_mfma_f32_16x16x32_bf16 v[42:45], v[150:153], v[186:189], v[42:45]
	v_mfma_f32_16x16x32_bf16 v[42:45], v[154:157], v[190:193], v[42:45]
	v_mfma_f32_16x16x32_bf16 v[46:49], v[142:145], v[186:189], v[46:49]
	v_mfma_f32_16x16x32_bf16 v[46:49], v[146:149], v[190:193], v[46:49]
	v_mfma_f32_16x16x32_bf16 v[30:33], v[142:145], v[194:197], v[30:33]
	v_mfma_f32_16x16x32_bf16 v[30:33], v[146:149], v[198:201], v[30:33]
	v_mfma_f32_16x16x32_bf16 v[26:29], v[150:153], v[194:197], v[26:29]
	v_mfma_f32_16x16x32_bf16 v[26:29], v[154:157], v[198:201], v[26:29]
	v_mfma_f32_16x16x32_bf16 v[10:13], v[150:153], v[202:205], v[10:13]
	v_mfma_f32_16x16x32_bf16 v[10:13], v[154:157], v[206:209], v[10:13]
	v_mfma_f32_16x16x32_bf16 v[14:17], v[142:145], v[202:205], v[14:17]
	v_mfma_f32_16x16x32_bf16 v[14:17], v[146:149], v[206:209], v[14:17]
	v_mfma_f32_16x16x32_bf16 v[54:57], v[162:165], v[178:181], v[54:57]
	v_mfma_f32_16x16x32_bf16 v[54:57], v[166:169], v[182:185], v[54:57]
	v_mfma_f32_16x16x32_bf16 v[50:53], v[170:173], v[178:181], v[50:53]
	v_mfma_f32_16x16x32_bf16 v[50:53], v[174:177], v[182:185], v[50:53]
	v_mfma_f32_16x16x32_bf16 v[34:37], v[170:173], v[186:189], v[34:37]
	v_mfma_f32_16x16x32_bf16 v[34:37], v[174:177], v[190:193], v[34:37]
	v_mfma_f32_16x16x32_bf16 v[38:41], v[162:165], v[186:189], v[38:41]
	v_mfma_f32_16x16x32_bf16 v[38:41], v[166:169], v[190:193], v[38:41]
	v_mfma_f32_16x16x32_bf16 v[22:25], v[162:165], v[194:197], v[22:25]
	v_mfma_f32_16x16x32_bf16 v[22:25], v[166:169], v[198:201], v[22:25]
	v_mfma_f32_16x16x32_bf16 v[18:21], v[170:173], v[194:197], v[18:21]
	v_mfma_f32_16x16x32_bf16 v[18:21], v[174:177], v[198:201], v[18:21]
	v_mfma_f32_16x16x32_bf16 v[2:5], v[170:173], v[202:205], v[2:5]
	v_mfma_f32_16x16x32_bf16 v[2:5], v[174:177], v[206:209], v[2:5]
	v_mfma_f32_16x16x32_bf16 v[6:9], v[162:165], v[202:205], v[6:9]
	v_mfma_f32_16x16x32_bf16 v[6:9], v[166:169], v[206:209], v[6:9]
	s_barrier
	s_setprio 0
	s_add_i32 s41, 0, 0x18000
	v_add_u32_e32 v0, s41, v159
	s_add_i32 s57, 0, 0x1c000
	ds_read_b128 v[142:145], v0
	ds_read_b128 v[146:149], v0 offset:1024
	ds_read_b128 v[150:153], v0 offset:2048
	ds_read_b128 v[154:157], v0 offset:3072
	v_add_u32_e32 v0, s57, v159
	ds_read_b128 v[162:165], v0
	ds_read_b128 v[166:169], v0 offset:1024
	ds_read_b128 v[170:173], v0 offset:2048
	ds_read_b128 v[174:177], v0 offset:3072
	s_add_u32 s30, s30, 0x80000
	s_addc_u32 s31, s31, 0
	s_mov_b32 m0, s47
	v_lshl_add_u64 v[218:219], s[30:31], 0, v[136:137]
	ds_read_b128 v[178:181], v161 offset:32768
	ds_read_b128 v[182:185], v161 offset:33792
	ds_read_b128 v[186:189], v161 offset:34816
	ds_read_b128 v[190:193], v161 offset:35840
	ds_read_b128 v[194:197], v161 offset:36864
	ds_read_b128 v[198:201], v161 offset:37888
	ds_read_b128 v[202:205], v161 offset:38912
	ds_read_b128 v[206:209], v161 offset:39936
	global_load_lds_dwordx4 v[218:219], off
	v_lshl_add_u64 v[218:219], s[30:31], 0, v[132:133]
	s_mov_b32 m0, s48
	s_nop 0
	global_load_lds_dwordx4 v[218:219], off
	s_waitcnt vmcnt(8)
	s_waitcnt lgkmcnt(0)
	s_setprio 1
	s_barrier
	v_mfma_f32_16x16x32_bf16 v[126:129], v[142:145], v[178:181], v[126:129]
	v_mfma_f32_16x16x32_bf16 v[126:129], v[146:149], v[182:185], v[126:129]
	v_mfma_f32_16x16x32_bf16 v[122:125], v[150:153], v[178:181], v[122:125]
	v_mfma_f32_16x16x32_bf16 v[122:125], v[154:157], v[182:185], v[122:125]
	v_mfma_f32_16x16x32_bf16 v[106:109], v[150:153], v[186:189], v[106:109]
	v_mfma_f32_16x16x32_bf16 v[106:109], v[154:157], v[190:193], v[106:109]
	v_mfma_f32_16x16x32_bf16 v[110:113], v[142:145], v[186:189], v[110:113]
	v_mfma_f32_16x16x32_bf16 v[110:113], v[146:149], v[190:193], v[110:113]
	v_mfma_f32_16x16x32_bf16 v[94:97], v[142:145], v[194:197], v[94:97]
	v_mfma_f32_16x16x32_bf16 v[94:97], v[146:149], v[198:201], v[94:97]
	v_mfma_f32_16x16x32_bf16 v[90:93], v[150:153], v[194:197], v[90:93]
	v_mfma_f32_16x16x32_bf16 v[90:93], v[154:157], v[198:201], v[90:93]
	v_mfma_f32_16x16x32_bf16 v[74:77], v[150:153], v[202:205], v[74:77]
	v_mfma_f32_16x16x32_bf16 v[74:77], v[154:157], v[206:209], v[74:77]
	v_mfma_f32_16x16x32_bf16 v[78:81], v[142:145], v[202:205], v[78:81]
	v_mfma_f32_16x16x32_bf16 v[78:81], v[146:149], v[206:209], v[78:81]
	v_mfma_f32_16x16x32_bf16 v[118:121], v[162:165], v[178:181], v[118:121]
	v_mfma_f32_16x16x32_bf16 v[118:121], v[166:169], v[182:185], v[118:121]
	v_mfma_f32_16x16x32_bf16 v[114:117], v[170:173], v[178:181], v[114:117]
	v_mfma_f32_16x16x32_bf16 v[114:117], v[174:177], v[182:185], v[114:117]
	v_mfma_f32_16x16x32_bf16 v[98:101], v[170:173], v[186:189], v[98:101]
	v_mfma_f32_16x16x32_bf16 v[98:101], v[174:177], v[190:193], v[98:101]
	v_mfma_f32_16x16x32_bf16 v[102:105], v[162:165], v[186:189], v[102:105]
	v_mfma_f32_16x16x32_bf16 v[102:105], v[166:169], v[190:193], v[102:105]
	v_mfma_f32_16x16x32_bf16 v[86:89], v[162:165], v[194:197], v[86:89]
	v_mfma_f32_16x16x32_bf16 v[86:89], v[166:169], v[198:201], v[86:89]
	v_mfma_f32_16x16x32_bf16 v[82:85], v[170:173], v[194:197], v[82:85]
	v_mfma_f32_16x16x32_bf16 v[82:85], v[174:177], v[198:201], v[82:85]
	v_mfma_f32_16x16x32_bf16 v[66:69], v[170:173], v[202:205], v[66:69]
	v_mfma_f32_16x16x32_bf16 v[66:69], v[174:177], v[206:209], v[66:69]
	v_mfma_f32_16x16x32_bf16 v[70:73], v[162:165], v[202:205], v[70:73]
	v_mfma_f32_16x16x32_bf16 v[70:73], v[166:169], v[206:209], v[70:73]
	s_barrier
; #define PG8_STAGE(bufoff, gbase, voff) do { _Pragma("unroll") for (int _i = 0; _i < 2; ++_i) \
;         __builtin_amdgcn_global_load_lds((const unsigned*)((const char*)(gbase) + (voff)[_i]), (LAS unsigned*)(lds + (bufoff) + ldsw + _i * 8192), 16, 0, 0); } while (0)
; #define PG8_LDA(dst, b, h) do { _Pragma("unroll") for (int m = 0; m < 4; ++m) _Pragma("unroll") for (int k = 0; k < 2; ++k) dst[m][k] = *(const LAS bf16x8*)(lds + PG8_SA(b, h) + aoff + m * 2048 + k * 1024); } while (0)
; #define PG8_MMA(ai, bj, At, Bt) do { __builtin_amdgcn_s_setprio(1); _Pragma("unroll") for (int m = 0; m < 4; ++m) _Pragma("unroll") for (int n = 0; n < 2; ++n) _Pragma("unroll") for (int k = 0; k < 2; ++k) \
;         acc[ai][bj][m][n] = __builtin_amdgcn_mfma_f32_16x16x32_bf16(Bt[n][k], At[m][k], acc[ai][bj][m][n], 0, 0, 0); __builtin_amdgcn_s_setprio(0); } while (0)
; #define PG8_WAIT_V(n) asm volatile("s_waitcnt vmcnt(" #n ")" ::: "memory")
; #define PG8_WAIT_L(n) asm volatile("s_waitcnt lgkmcnt(" #n ")" ::: "memory")
; #define PG8_BAR __builtin_amdgcn_s_barrier()
; #define PG8_SCHED __builtin_amdgcn_sched_barrier(0)
; template <class Epi, class Sched, bool ALIGN_EPI = false, bool SP2 = false>
; __device__ __forceinline__ void gemm_phase(LAS unsigned char* lds, const Gemm g, const Sched& S, const Epi& E) {
;     ...
;             PG8_LDA(At, 1, 1); PG8_STAGE(PG8_SB(1, 0), b3, voffB); PG8_STAGE(PG8_SB(1, 1), b3 + hstep, voffB); PG8_STAGE(PG8_SA(1, 0), a3, voffA);
;             PG8_WAIT_V(8); PG8_WAIT_L(0); PG8_BAR; PG8_MMA(1, 0, At, B0); PG8_MMA(1, 1, At, B1); PG8_BAR; PG8_SCHED;
;     ...
;         if constexpr (ALIGN_EPI) { if (wr == 0) PG8_BAR; }
	s_setprio 0
	s_add_i32 s30, s41, s9
	v_lshl_add_u64 v[210:211], v[210:211], 0, s[12:13]
	s_mov_b32 m0, s30
	ds_read_b128 v[178:181], v161 offset:49152
	ds_read_b128 v[182:185], v161 offset:50176
	ds_read_b128 v[186:189], v161 offset:51200
	ds_read_b128 v[190:193], v161 offset:52224
	ds_read_b128 v[194:197], v161 offset:53248
	ds_read_b128 v[198:201], v161 offset:54272
	ds_read_b128 v[202:205], v161 offset:55296
	ds_read_b128 v[206:209], v161 offset:56320
	global_load_lds_dwordx4 v[210:211], off
	s_add_i32 m0, s30, 0x2000
	s_add_u32 s28, s28, 0x80080
	v_lshl_add_u64 v[210:211], v[212:213], 0, s[12:13]
	s_addc_u32 s29, s29, 0
	s_add_i32 s30, s57, s9
	global_load_lds_dwordx4 v[210:211], off
	v_lshl_add_u64 v[210:211], s[28:29], 0, v[134:135]
	s_mov_b32 m0, s30
	s_nop 0
	global_load_lds_dwordx4 v[210:211], off
	v_lshl_add_u64 v[210:211], s[28:29], 0, v[130:131]
	s_add_i32 m0, s30, 0x2000
	s_nop 0
	global_load_lds_dwordx4 v[210:211], off
	v_lshl_add_u64 v[210:211], v[214:215], 0, s[12:13]
	s_mov_b32 m0, s53
	s_nop 0
	global_load_lds_dwordx4 v[210:211], off
	v_lshl_add_u64 v[210:211], v[216:217], 0, s[12:13]
	s_mov_b32 m0, s54
	s_nop 0
	global_load_lds_dwordx4 v[210:211], off
	s_waitcnt vmcnt(8)
	s_waitcnt lgkmcnt(0)
	s_setprio 1
	s_barrier
	v_mfma_f32_16x16x32_bf16 v[62:65], v[142:145], v[178:181], v[62:65]
	v_mfma_f32_16x16x32_bf16 v[62:65], v[146:149], v[182:185], v[62:65]
	v_mfma_f32_16x16x32_bf16 v[58:61], v[150:153], v[178:181], v[58:61]
	v_mfma_f32_16x16x32_bf16 v[58:61], v[154:157], v[182:185], v[58:61]
	v_mfma_f32_16x16x32_bf16 v[42:45], v[150:153], v[186:189], v[42:45]
	v_mfma_f32_16x16x32_bf16 v[42:45], v[154:157], v[190:193], v[42:45]
	v_mfma_f32_16x16x32_bf16 v[46:49], v[142:145], v[186:189], v[46:49]
	v_mfma_f32_16x16x32_bf16 v[46:49], v[146:149], v[190:193], v[46:49]
	v_mfma_f32_16x16x32_bf16 v[30:33], v[142:145], v[194:197], v[30:33]
	v_mfma_f32_16x16x32_bf16 v[30:33], v[146:149], v[198:201], v[30:33]
	v_mfma_f32_16x16x32_bf16 v[26:29], v[150:153], v[194:197], v[26:29]
	v_mfma_f32_16x16x32_bf16 v[26:29], v[154:157], v[198:201], v[26:29]
	v_mfma_f32_16x16x32_bf16 v[10:13], v[150:153], v[202:205], v[10:13]
	v_mfma_f32_16x16x32_bf16 v[10:13], v[154:157], v[206:209], v[10:13]
	v_mfma_f32_16x16x32_bf16 v[14:17], v[142:145], v[202:205], v[14:17]
	v_mfma_f32_16x16x32_bf16 v[14:17], v[146:149], v[206:209], v[14:17]
	v_mfma_f32_16x16x32_bf16 v[54:57], v[162:165], v[178:181], v[54:57]
	v_mfma_f32_16x16x32_bf16 v[54:57], v[166:169], v[182:185], v[54:57]
	v_mfma_f32_16x16x32_bf16 v[50:53], v[170:173], v[178:181], v[50:53]
	v_mfma_f32_16x16x32_bf16 v[50:53], v[174:177], v[182:185], v[50:53]
	v_mfma_f32_16x16x32_bf16 v[34:37], v[170:173], v[186:189], v[34:37]
	v_mfma_f32_16x16x32_bf16 v[34:37], v[174:177], v[190:193], v[34:37]
	v_mfma_f32_16x16x32_bf16 v[38:41], v[162:165], v[186:189], v[38:41]
	v_mfma_f32_16x16x32_bf16 v[38:41], v[166:169], v[190:193], v[38:41]
	v_mfma_f32_16x16x32_bf16 v[22:25], v[162:165], v[194:197], v[22:25]
	v_mfma_f32_16x16x32_bf16 v[22:25], v[166:169], v[198:201], v[22:25]
	v_mfma_f32_16x16x32_bf16 v[18:21], v[170:173], v[194:197], v[18:21]
	v_mfma_f32_16x16x32_bf16 v[18:21], v[174:177], v[198:201], v[18:21]
	v_mfma_f32_16x16x32_bf16 v[2:5], v[170:173], v[202:205], v[2:5]
	v_mfma_f32_16x16x32_bf16 v[2:5], v[174:177], v[206:209], v[2:5]
	v_mfma_f32_16x16x32_bf16 v[6:9], v[162:165], v[202:205], v[6:9]
	v_mfma_f32_16x16x32_bf16 v[6:9], v[166:169], v[206:209], v[6:9]
	s_barrier
	s_setprio 0
	s_add_i32 s40, s40, 2
	s_add_u32 s26, s26, 0x100
	s_addc_u32 s27, s27, 0
	s_add_u32 s21, s21, 0x100
	s_addc_u32 s35, s35, 0
	s_cmp_gt_u32 s40, 29
	s_cbranch_scc0 .LBB0_359
	s_and_b64 vcc, exec, s[16:17]
	s_cbranch_vccz .LBB0_362
	s_barrier
	s_setprio 1

; #define PG8_STAGE(bufoff, gbase, voff) do { _Pragma("unroll") for (int _i = 0; _i < 2; ++_i) \
;         __builtin_amdgcn_global_load_lds((const unsigned*)((const char*)(gbase) + (voff)[_i]), (LAS unsigned*)(lds + (bufoff) + ldsw + _i * 8192), 16, 0, 0); } while (0)
; #define PG8_LDA(dst, b, h) do { _Pragma("unroll") for (int m = 0; m < 4; ++m) _Pragma("unroll") for (int k = 0; k < 2; ++k) dst[m][k] = *(const LAS bf16x8*)(lds + PG8_SA(b, h) + aoff + m * 2048 + k * 1024); } while (0)
; #define PG8_LDB(dst, b, h) do { _Pragma("unroll") for (int n = 0; n < 2; ++n) _Pragma("unroll") for (int k = 0; k < 2; ++k) dst[n][k] = *(const LAS bf16x8*)(lds + PG8_SB(b, h) + boff + n * 2048 + k * 1024); } while (0)
; #define PG8_MMA(ai, bj, At, Bt) do { __builtin_amdgcn_s_setprio(1); _Pragma("unroll") for (int m = 0; m < 4; ++m) _Pragma("unroll") for (int n = 0; n < 2; ++n) _Pragma("unroll") for (int k = 0; k < 2; ++k) \
;         acc[ai][bj][m][n] = __builtin_amdgcn_mfma_f32_16x16x32_bf16(Bt[n][k], At[m][k], acc[ai][bj][m][n], 0, 0, 0); __builtin_amdgcn_s_setprio(0); } while (0)
; template <class Epi, class Sched, bool ALIGN_EPI = false, bool SP2 = false>
; __device__ __forceinline__ void gemm_phase(LAS unsigned char* lds, const Gemm g, const Sched& S, const Epi& E) {
;     ...
;         const char* nA = has_next ? (const char*)g.A + (size_t)nxt.pm * tstep : cA; const char* nB = has_next ? (const char*)g.Bt + (size_t)nxt.pn * tstep : cB;
;         for (int t = 0; t < nt; t += 2) {
;             const bool last = (t == nt - 2);
;             const char* a1 = cA + (size_t)(t + 1) * kstep;
;             const char* a2 = last ? nA : cA + (size_t)(t + 2) * kstep; const char* b2 = last ? nB : cB + (size_t)(t + 2) * kstep;
;             const char* a3 = a2 + kstep; const char* b3 = b2 + kstep;
;             if (last && has_next) S.a_ready(nxt);
;             if constexpr (SP2) {
;             PG8_LDB(B0, 0, 0); PG8_LDB(B1, 0, 1); PG8_SCHED; PG8_LDA(At, 0, 0); PG8_STAGE(PG8_SA(1, 1), a1 + hstep, voffA);
;             PG8_WAIT_V(8); PG8_WAIT_L(0); PG8_BAR; PG8_MMA(0, 0, At, B0); PG8_MMA(0, 1, At, B1); PG8_BAR; PG8_SCHED;
;             PG8_LDA(At, 0, 1); PG8_STAGE(PG8_SB(0, 0), b2, voffB); PG8_STAGE(PG8_SB(0, 1), b2 + hstep, voffB); PG8_STAGE(PG8_SA(0, 0), a2, voffA);
;             PG8_WAIT_V(8); PG8_WAIT_L(0); PG8_BAR; PG8_MMA(1, 0, At, B0); PG8_MMA(1, 1, At, B1); PG8_BAR; PG8_SCHED;
.LBB0_833:
	s_add_u32 s28, s26, 0xfff80080
	s_addc_u32 s29, s27, -1
	s_add_i32 s53, 0, 0x10000
	s_cmp_eq_u32 s52, 28
	s_cselect_b32 s31, s21, s29
	s_cselect_b32 s30, s48, s28
	s_cselect_b32 s29, s19, s51
	s_cselect_b32 s28, s49, s50
	s_add_i32 s56, 0, 0x14000
	v_add_u32_e32 v134, s53, v247
	v_add_u32_e32 v158, s56, v247
	ds_read_b128 v[106:109], v134
	ds_read_b128 v[110:113], v134 offset:1024
	ds_read_b128 v[122:125], v134 offset:2048
	ds_read_b128 v[134:137], v134 offset:3072
	ds_read_b128 v[146:149], v158
	ds_read_b128 v[150:153], v158 offset:1024
	ds_read_b128 v[154:157], v158 offset:2048
	ds_read_b128 v[158:161], v158 offset:3072
	v_lshl_add_u64 v[204:205], s[26:27], 0, v[200:201]
	s_add_i32 m0, s8, 0xc000
	ds_read_b128 v[162:165], v249
	ds_read_b128 v[166:169], v249 offset:1024
	ds_read_b128 v[170:173], v249 offset:2048
	ds_read_b128 v[174:177], v249 offset:3072
	ds_read_b128 v[178:181], v249 offset:4096
	ds_read_b128 v[182:185], v249 offset:5120
	ds_read_b128 v[186:189], v249 offset:6144
	ds_read_b128 v[190:193], v249 offset:7168
	global_load_lds_dwordx4 v[204:205], off
	v_lshl_add_u64 v[204:205], s[26:27], 0, v[202:203]
	s_add_i32 m0, s8, 0xe000
	s_nop 0
	global_load_lds_dwordx4 v[204:205], off
	s_waitcnt vmcnt(8)
	s_waitcnt lgkmcnt(0)
	s_setprio 1
	s_barrier
	v_mfma_f32_16x16x32_bf16 v[142:145], v[106:109], v[162:165], v[142:145]
	v_mfma_f32_16x16x32_bf16 v[142:145], v[110:113], v[166:169], v[142:145]
	v_mfma_f32_16x16x32_bf16 v[138:141], v[122:125], v[162:165], v[138:141]
	v_mfma_f32_16x16x32_bf16 v[138:141], v[134:137], v[166:169], v[138:141]
	v_mfma_f32_16x16x32_bf16 v[114:117], v[122:125], v[170:173], v[114:117]
	v_mfma_f32_16x16x32_bf16 v[114:117], v[134:137], v[174:177], v[114:117]
	v_mfma_f32_16x16x32_bf16 v[118:121], v[106:109], v[170:173], v[118:121]
	v_mfma_f32_16x16x32_bf16 v[118:121], v[110:113], v[174:177], v[118:121]
	v_mfma_f32_16x16x32_bf16 v[94:97], v[106:109], v[178:181], v[94:97]
	v_mfma_f32_16x16x32_bf16 v[94:97], v[110:113], v[182:185], v[94:97]
	v_mfma_f32_16x16x32_bf16 v[90:93], v[122:125], v[178:181], v[90:93]
	v_mfma_f32_16x16x32_bf16 v[90:93], v[134:137], v[182:185], v[90:93]
	v_mfma_f32_16x16x32_bf16 v[74:77], v[122:125], v[186:189], v[74:77]
	v_mfma_f32_16x16x32_bf16 v[74:77], v[134:137], v[190:193], v[74:77]
	v_mfma_f32_16x16x32_bf16 v[78:81], v[106:109], v[186:189], v[78:81]
	v_mfma_f32_16x16x32_bf16 v[78:81], v[110:113], v[190:193], v[78:81]
	v_mfma_f32_16x16x32_bf16 v[130:133], v[146:149], v[162:165], v[130:133]
	v_mfma_f32_16x16x32_bf16 v[130:133], v[150:153], v[166:169], v[130:133]
	v_mfma_f32_16x16x32_bf16 v[126:129], v[154:157], v[162:165], v[126:129]
	v_mfma_f32_16x16x32_bf16 v[126:129], v[158:161], v[166:169], v[126:129]
	v_mfma_f32_16x16x32_bf16 v[98:101], v[154:157], v[170:173], v[98:101]
	v_mfma_f32_16x16x32_bf16 v[98:101], v[158:161], v[174:177], v[98:101]
	v_mfma_f32_16x16x32_bf16 v[102:105], v[146:149], v[170:173], v[102:105]
	v_mfma_f32_16x16x32_bf16 v[102:105], v[150:153], v[174:177], v[102:105]
	v_mfma_f32_16x16x32_bf16 v[86:89], v[146:149], v[178:181], v[86:89]
	v_mfma_f32_16x16x32_bf16 v[86:89], v[150:153], v[182:185], v[86:89]
	v_mfma_f32_16x16x32_bf16 v[82:85], v[154:157], v[178:181], v[82:85]
	v_mfma_f32_16x16x32_bf16 v[82:85], v[158:161], v[182:185], v[82:85]
	v_mfma_f32_16x16x32_bf16 v[66:69], v[154:157], v[186:189], v[66:69]
	v_mfma_f32_16x16x32_bf16 v[66:69], v[158:161], v[190:193], v[66:69]
	v_mfma_f32_16x16x32_bf16 v[70:73], v[146:149], v[186:189], v[70:73]
	v_mfma_f32_16x16x32_bf16 v[70:73], v[150:153], v[190:193], v[70:73]
	s_barrier
	s_setprio 0
	s_add_i32 s53, s53, s7
	v_lshl_add_u64 v[204:205], s[28:29], 0, v[0:1]
	s_mov_b32 m0, s53
	ds_read_b128 v[162:165], v249 offset:16384
	ds_read_b128 v[166:169], v249 offset:17408
	ds_read_b128 v[170:173], v249 offset:18432
	ds_read_b128 v[174:177], v249 offset:19456
	ds_read_b128 v[178:181], v249 offset:20480
	ds_read_b128 v[182:185], v249 offset:21504
	ds_read_b128 v[186:189], v249 offset:22528
	ds_read_b128 v[190:193], v249 offset:23552
	global_load_lds_dwordx4 v[204:205], off
	s_add_i32 m0, s53, 0x2000
	s_add_u32 s54, s28, 0x80000
	v_lshl_add_u64 v[206:207], s[28:29], 0, v[194:195]
	s_addc_u32 s55, s29, 0
	s_add_i32 s53, s56, s7
	global_load_lds_dwordx4 v[206:207], off
	v_lshl_add_u64 v[208:209], s[54:55], 0, v[0:1]
	s_mov_b32 m0, s53
	v_lshl_add_u64 v[210:211], s[30:31], 0, v[196:197]
	global_load_lds_dwordx4 v[208:209], off
	v_lshl_add_u64 v[208:209], s[54:55], 0, v[194:195]
	s_add_i32 m0, s53, 0x2000
	s_nop 0
	global_load_lds_dwordx4 v[208:209], off
	v_lshl_add_u64 v[208:209], s[30:31], 0, v[198:199]
	s_mov_b32 m0, s8
	s_nop 0
	global_load_lds_dwordx4 v[208:209], off
	s_mov_b32 m0, s9
	s_nop 0
	global_load_lds_dwordx4 v[210:211], off
	s_waitcnt vmcnt(8)
	s_waitcnt lgkmcnt(0)
	s_setprio 1
	s_barrier
; #define PG8_STAGE(bufoff, gbase, voff) do { _Pragma("unroll") for (int _i = 0; _i < 2; ++_i) \
;         __builtin_amdgcn_global_load_lds((const unsigned*)((const char*)(gbase) + (voff)[_i]), (LAS unsigned*)(lds + (bufoff) + ldsw + _i * 8192), 16, 0, 0); } while (0)
; #define PG8_LDA(dst, b, h) do { _Pragma("unroll") for (int m = 0; m < 4; ++m) _Pragma("unroll") for (int k = 0; k < 2; ++k) dst[m][k] = *(const LAS bf16x8*)(lds + PG8_SA(b, h) + aoff + m * 2048 + k * 1024); } while (0)
; #define PG8_LDB(dst, b, h) do { _Pragma("unroll") for (int n = 0; n < 2; ++n) _Pragma("unroll") for (int k = 0; k < 2; ++k) dst[n][k] = *(const LAS bf16x8*)(lds + PG8_SB(b, h) + boff + n * 2048 + k * 1024); } while (0)
; #define PG8_MMA(ai, bj, At, Bt) do { __builtin_amdgcn_s_setprio(1); _Pragma("unroll") for (int m = 0; m < 4; ++m) _Pragma("unroll") for (int n = 0; n < 2; ++n) _Pragma("unroll") for (int k = 0; k < 2; ++k) \
;         acc[ai][bj][m][n] = __builtin_amdgcn_mfma_f32_16x16x32_bf16(Bt[n][k], At[m][k], acc[ai][bj][m][n], 0, 0, 0); __builtin_amdgcn_s_setprio(0); } while (0)
; #define PG8_WAIT_V(n) asm volatile("s_waitcnt vmcnt(" #n ")" ::: "memory")
; #define PG8_WAIT_L(n) asm volatile("s_waitcnt lgkmcnt(" #n ")" ::: "memory")
; #define PG8_BAR __builtin_amdgcn_s_barrier()
; #define PG8_SCHED __builtin_amdgcn_sched_barrier(0)
; template <class Epi, class Sched, bool ALIGN_EPI = false, bool SP2 = false>
; __device__ __forceinline__ void gemm_phase(LAS unsigned char* lds, const Gemm g, const Sched& S, const Epi& E) {
;     ...
;             PG8_WAIT_V(8); PG8_WAIT_L(0); PG8_BAR; PG8_MMA(1, 0, At, B0); PG8_MMA(1, 1, At, B1); PG8_BAR; PG8_SCHED;
;             PG8_LDB(B0, 1, 0); PG8_LDB(B1, 1, 1); PG8_SCHED; PG8_LDA(At, 1, 0); PG8_STAGE(PG8_SA(0, 1), a2 + hstep, voffA);
;             PG8_WAIT_V(8); PG8_WAIT_L(0); PG8_BAR; PG8_MMA(0, 0, At, B0); PG8_MMA(0, 1, At, B1); PG8_BAR; PG8_SCHED;
	v_mfma_f32_16x16x32_bf16 v[62:65], v[106:109], v[162:165], v[62:65]
	v_mfma_f32_16x16x32_bf16 v[62:65], v[110:113], v[166:169], v[62:65]
	v_mfma_f32_16x16x32_bf16 v[58:61], v[122:125], v[162:165], v[58:61]
	v_mfma_f32_16x16x32_bf16 v[58:61], v[134:137], v[166:169], v[58:61]
	v_mfma_f32_16x16x32_bf16 v[42:45], v[122:125], v[170:173], v[42:45]
	v_mfma_f32_16x16x32_bf16 v[42:45], v[134:137], v[174:177], v[42:45]
	v_mfma_f32_16x16x32_bf16 v[46:49], v[106:109], v[170:173], v[46:49]
	v_mfma_f32_16x16x32_bf16 v[46:49], v[110:113], v[174:177], v[46:49]
	v_mfma_f32_16x16x32_bf16 v[30:33], v[106:109], v[178:181], v[30:33]
	v_mfma_f32_16x16x32_bf16 v[30:33], v[110:113], v[182:185], v[30:33]
	v_mfma_f32_16x16x32_bf16 v[26:29], v[122:125], v[178:181], v[26:29]
	v_mfma_f32_16x16x32_bf16 v[26:29], v[134:137], v[182:185], v[26:29]
	v_mfma_f32_16x16x32_bf16 v[10:13], v[122:125], v[186:189], v[10:13]
	v_mfma_f32_16x16x32_bf16 v[10:13], v[134:137], v[190:193], v[10:13]
	v_mfma_f32_16x16x32_bf16 v[14:17], v[106:109], v[186:189], v[14:17]
	v_mfma_f32_16x16x32_bf16 v[14:17], v[110:113], v[190:193], v[14:17]
	v_mfma_f32_16x16x32_bf16 v[54:57], v[146:149], v[162:165], v[54:57]
	v_mfma_f32_16x16x32_bf16 v[54:57], v[150:153], v[166:169], v[54:57]
	v_mfma_f32_16x16x32_bf16 v[50:53], v[154:157], v[162:165], v[50:53]
	v_mfma_f32_16x16x32_bf16 v[50:53], v[158:161], v[166:169], v[50:53]
	v_mfma_f32_16x16x32_bf16 v[34:37], v[154:157], v[170:173], v[34:37]
	v_mfma_f32_16x16x32_bf16 v[34:37], v[158:161], v[174:177], v[34:37]
	v_mfma_f32_16x16x32_bf16 v[38:41], v[146:149], v[170:173], v[38:41]
	v_mfma_f32_16x16x32_bf16 v[38:41], v[150:153], v[174:177], v[38:41]
	v_mfma_f32_16x16x32_bf16 v[22:25], v[146:149], v[178:181], v[22:25]
	v_mfma_f32_16x16x32_bf16 v[22:25], v[150:153], v[182:185], v[22:25]
	v_mfma_f32_16x16x32_bf16 v[18:21], v[154:157], v[178:181], v[18:21]
	v_mfma_f32_16x16x32_bf16 v[18:21], v[158:161], v[182:185], v[18:21]
	v_mfma_f32_16x16x32_bf16 v[2:5], v[154:157], v[186:189], v[2:5]
	v_mfma_f32_16x16x32_bf16 v[2:5], v[158:161], v[190:193], v[2:5]
	v_mfma_f32_16x16x32_bf16 v[6:9], v[146:149], v[186:189], v[6:9]
	v_mfma_f32_16x16x32_bf16 v[6:9], v[150:153], v[190:193], v[6:9]
	s_barrier
	s_setprio 0
	s_add_i32 s53, 0, 0x18000
	s_add_i32 s54, 0, 0x1c000
	v_add_u32_e32 v134, s53, v247
	v_add_u32_e32 v158, s54, v247
	ds_read_b128 v[106:109], v134
	ds_read_b128 v[110:113], v134 offset:1024
	ds_read_b128 v[122:125], v134 offset:2048
	ds_read_b128 v[134:137], v134 offset:3072
	ds_read_b128 v[146:149], v158
	ds_read_b128 v[150:153], v158 offset:1024
	ds_read_b128 v[154:157], v158 offset:2048
	ds_read_b128 v[158:161], v158 offset:3072
	s_add_u32 s30, s30, 0x80000
	s_addc_u32 s31, s31, 0
	s_mov_b32 m0, s35
	v_lshl_add_u64 v[212:213], s[30:31], 0, v[198:199]
	ds_read_b128 v[162:165], v249 offset:32768
	ds_read_b128 v[166:169], v249 offset:33792
	ds_read_b128 v[170:173], v249 offset:34816
	ds_read_b128 v[174:177], v249 offset:35840
	ds_read_b128 v[178:181], v249 offset:36864
	ds_read_b128 v[182:185], v249 offset:37888
	ds_read_b128 v[186:189], v249 offset:38912
	ds_read_b128 v[190:193], v249 offset:39936
	global_load_lds_dwordx4 v[212:213], off
	v_lshl_add_u64 v[212:213], s[30:31], 0, v[196:197]
	s_mov_b32 m0, s42
	s_nop 0
	global_load_lds_dwordx4 v[212:213], off
	s_waitcnt vmcnt(8)
	s_waitcnt lgkmcnt(0)
	s_setprio 1
	s_barrier
	v_mfma_f32_16x16x32_bf16 v[142:145], v[106:109], v[162:165], v[142:145]
	v_mfma_f32_16x16x32_bf16 v[142:145], v[110:113], v[166:169], v[142:145]
	v_mfma_f32_16x16x32_bf16 v[138:141], v[122:125], v[162:165], v[138:141]
	v_mfma_f32_16x16x32_bf16 v[138:141], v[134:137], v[166:169], v[138:141]
	v_mfma_f32_16x16x32_bf16 v[114:117], v[122:125], v[170:173], v[114:117]
	v_mfma_f32_16x16x32_bf16 v[114:117], v[134:137], v[174:177], v[114:117]
	v_mfma_f32_16x16x32_bf16 v[118:121], v[106:109], v[170:173], v[118:121]
	v_mfma_f32_16x16x32_bf16 v[118:121], v[110:113], v[174:177], v[118:121]
	v_mfma_f32_16x16x32_bf16 v[94:97], v[106:109], v[178:181], v[94:97]
	v_mfma_f32_16x16x32_bf16 v[94:97], v[110:113], v[182:185], v[94:97]
	v_mfma_f32_16x16x32_bf16 v[90:93], v[122:125], v[178:181], v[90:93]
	v_mfma_f32_16x16x32_bf16 v[90:93], v[134:137], v[182:185], v[90:93]
	v_mfma_f32_16x16x32_bf16 v[74:77], v[122:125], v[186:189], v[74:77]
	v_mfma_f32_16x16x32_bf16 v[74:77], v[134:137], v[190:193], v[74:77]
	v_mfma_f32_16x16x32_bf16 v[78:81], v[106:109], v[186:189], v[78:81]
	v_mfma_f32_16x16x32_bf16 v[78:81], v[110:113], v[190:193], v[78:81]
	v_mfma_f32_16x16x32_bf16 v[130:133], v[146:149], v[162:165], v[130:133]
	v_mfma_f32_16x16x32_bf16 v[130:133], v[150:153], v[166:169], v[130:133]
	v_mfma_f32_16x16x32_bf16 v[126:129], v[154:157], v[162:165], v[126:129]
	v_mfma_f32_16x16x32_bf16 v[126:129], v[158:161], v[166:169], v[126:129]
	v_mfma_f32_16x16x32_bf16 v[98:101], v[154:157], v[170:173], v[98:101]
	v_mfma_f32_16x16x32_bf16 v[98:101], v[158:161], v[174:177], v[98:101]
	v_mfma_f32_16x16x32_bf16 v[102:105], v[146:149], v[170:173], v[102:105]
	v_mfma_f32_16x16x32_bf16 v[102:105], v[150:153], v[174:177], v[102:105]
	v_mfma_f32_16x16x32_bf16 v[86:89], v[146:149], v[178:181], v[86:89]
	v_mfma_f32_16x16x32_bf16 v[86:89], v[150:153], v[182:185], v[86:89]
	v_mfma_f32_16x16x32_bf16 v[82:85], v[154:157], v[178:181], v[82:85]
	v_mfma_f32_16x16x32_bf16 v[82:85], v[158:161], v[182:185], v[82:85]
	v_mfma_f32_16x16x32_bf16 v[66:69], v[154:157], v[186:189], v[66:69]
	v_mfma_f32_16x16x32_bf16 v[66:69], v[158:161], v[190:193], v[66:69]
	v_mfma_f32_16x16x32_bf16 v[70:73], v[146:149], v[186:189], v[70:73]
	v_mfma_f32_16x16x32_bf16 v[70:73], v[150:153], v[190:193], v[70:73]
	s_barrier
; #define PG8_STAGE(bufoff, gbase, voff) do { _Pragma("unroll") for (int _i = 0; _i < 2; ++_i) \
;         __builtin_amdgcn_global_load_lds((const unsigned*)((const char*)(gbase) + (voff)[_i]), (LAS unsigned*)(lds + (bufoff) + ldsw + _i * 8192), 16, 0, 0); } while (0)
; #define PG8_LDA(dst, b, h) do { _Pragma("unroll") for (int m = 0; m < 4; ++m) _Pragma("unroll") for (int k = 0; k < 2; ++k) dst[m][k] = *(const LAS bf16x8*)(lds + PG8_SA(b, h) + aoff + m * 2048 + k * 1024); } while (0)
; #define PG8_MMA(ai, bj, At, Bt) do { __builtin_amdgcn_s_setprio(1); _Pragma("unroll") for (int m = 0; m < 4; ++m) _Pragma("unroll") for (int n = 0; n < 2; ++n) _Pragma("unroll") for (int k = 0; k < 2; ++k) \
;         acc[ai][bj][m][n] = __builtin_amdgcn_mfma_f32_16x16x32_bf16(Bt[n][k], At[m][k], acc[ai][bj][m][n], 0, 0, 0); __builtin_amdgcn_s_setprio(0); } while (0)
; #define PG8_WAIT_V(n) asm volatile("s_waitcnt vmcnt(" #n ")" ::: "memory")
; #define PG8_WAIT_L(n) asm volatile("s_waitcnt lgkmcnt(" #n ")" ::: "memory")
; #define PG8_BAR __builtin_amdgcn_s_barrier()
; #define PG8_SCHED __builtin_amdgcn_sched_barrier(0)
; template <class Epi, class Sched, bool ALIGN_EPI = false, bool SP2 = false>
; __device__ __forceinline__ void gemm_phase(LAS unsigned char* lds, const Gemm g, const Sched& S, const Epi& E) {
;     ...
;             PG8_LDA(At, 1, 1); PG8_STAGE(PG8_SB(1, 0), b3, voffB); PG8_STAGE(PG8_SB(1, 1), b3 + hstep, voffB); PG8_STAGE(PG8_SA(1, 0), a3, voffA);
;             PG8_WAIT_V(8); PG8_WAIT_L(0); PG8_BAR; PG8_MMA(1, 0, At, B0); PG8_MMA(1, 1, At, B1); PG8_BAR; PG8_SCHED;
;     ...
;         if constexpr (ALIGN_EPI) { if (wr == 0) PG8_BAR; }
	s_setprio 0
	s_add_i32 s30, s53, s7
	v_lshl_add_u64 v[204:205], v[204:205], 0, s[12:13]
	s_mov_b32 m0, s30
	ds_read_b128 v[162:165], v249 offset:49152
	ds_read_b128 v[166:169], v249 offset:50176
	ds_read_b128 v[170:173], v249 offset:51200
	ds_read_b128 v[174:177], v249 offset:52224
	ds_read_b128 v[178:181], v249 offset:53248
	ds_read_b128 v[182:185], v249 offset:54272
	ds_read_b128 v[186:189], v249 offset:55296
	ds_read_b128 v[190:193], v249 offset:56320
	global_load_lds_dwordx4 v[204:205], off
	s_add_i32 m0, s30, 0x2000
	s_add_u32 s28, s28, 0x80080
	v_lshl_add_u64 v[204:205], v[206:207], 0, s[12:13]
	s_addc_u32 s29, s29, 0
	s_add_i32 s30, s54, s7
	global_load_lds_dwordx4 v[204:205], off
	v_lshl_add_u64 v[204:205], s[28:29], 0, v[0:1]
	s_mov_b32 m0, s30
	s_nop 0
	global_load_lds_dwordx4 v[204:205], off
	v_lshl_add_u64 v[204:205], s[28:29], 0, v[194:195]
	s_add_i32 m0, s30, 0x2000
	s_nop 0
	global_load_lds_dwordx4 v[204:205], off
	v_lshl_add_u64 v[204:205], v[208:209], 0, s[12:13]
	s_mov_b32 m0, s43
	s_nop 0
	global_load_lds_dwordx4 v[204:205], off
	v_lshl_add_u64 v[204:205], v[210:211], 0, s[12:13]
	s_mov_b32 m0, s44
	s_nop 0
	global_load_lds_dwordx4 v[204:205], off
	s_waitcnt vmcnt(8)
	s_waitcnt lgkmcnt(0)
	s_setprio 1
	s_barrier
	v_mfma_f32_16x16x32_bf16 v[62:65], v[106:109], v[162:165], v[62:65]
	v_mfma_f32_16x16x32_bf16 v[62:65], v[110:113], v[166:169], v[62:65]
	v_mfma_f32_16x16x32_bf16 v[58:61], v[122:125], v[162:165], v[58:61]
	v_mfma_f32_16x16x32_bf16 v[58:61], v[134:137], v[166:169], v[58:61]
	v_mfma_f32_16x16x32_bf16 v[42:45], v[122:125], v[170:173], v[42:45]
	v_mfma_f32_16x16x32_bf16 v[42:45], v[134:137], v[174:177], v[42:45]
	v_mfma_f32_16x16x32_bf16 v[46:49], v[106:109], v[170:173], v[46:49]
	v_mfma_f32_16x16x32_bf16 v[46:49], v[110:113], v[174:177], v[46:49]
	v_mfma_f32_16x16x32_bf16 v[30:33], v[106:109], v[178:181], v[30:33]
	v_mfma_f32_16x16x32_bf16 v[30:33], v[110:113], v[182:185], v[30:33]
	v_mfma_f32_16x16x32_bf16 v[26:29], v[122:125], v[178:181], v[26:29]
	v_mfma_f32_16x16x32_bf16 v[26:29], v[134:137], v[182:185], v[26:29]
	v_mfma_f32_16x16x32_bf16 v[10:13], v[122:125], v[186:189], v[10:13]
	v_mfma_f32_16x16x32_bf16 v[10:13], v[134:137], v[190:193], v[10:13]
	v_mfma_f32_16x16x32_bf16 v[14:17], v[106:109], v[186:189], v[14:17]
	v_mfma_f32_16x16x32_bf16 v[14:17], v[110:113], v[190:193], v[14:17]
	v_mfma_f32_16x16x32_bf16 v[54:57], v[146:149], v[162:165], v[54:57]
	v_mfma_f32_16x16x32_bf16 v[54:57], v[150:153], v[166:169], v[54:57]
	v_mfma_f32_16x16x32_bf16 v[50:53], v[154:157], v[162:165], v[50:53]
	v_mfma_f32_16x16x32_bf16 v[50:53], v[158:161], v[166:169], v[50:53]
	v_mfma_f32_16x16x32_bf16 v[34:37], v[154:157], v[170:173], v[34:37]
	v_mfma_f32_16x16x32_bf16 v[34:37], v[158:161], v[174:177], v[34:37]
	v_mfma_f32_16x16x32_bf16 v[38:41], v[146:149], v[170:173], v[38:41]
	v_mfma_f32_16x16x32_bf16 v[38:41], v[150:153], v[174:177], v[38:41]
	v_mfma_f32_16x16x32_bf16 v[22:25], v[146:149], v[178:181], v[22:25]
	v_mfma_f32_16x16x32_bf16 v[22:25], v[150:153], v[182:185], v[22:25]
	v_mfma_f32_16x16x32_bf16 v[18:21], v[154:157], v[178:181], v[18:21]
	v_mfma_f32_16x16x32_bf16 v[18:21], v[158:161], v[182:185], v[18:21]
	v_mfma_f32_16x16x32_bf16 v[2:5], v[154:157], v[186:189], v[2:5]
	v_mfma_f32_16x16x32_bf16 v[2:5], v[158:161], v[190:193], v[2:5]
	v_mfma_f32_16x16x32_bf16 v[6:9], v[146:149], v[186:189], v[6:9]
	v_mfma_f32_16x16x32_bf16 v[6:9], v[150:153], v[190:193], v[6:9]
	s_barrier
	s_setprio 0
	s_add_i32 s52, s52, 2
	s_add_u32 s26, s26, 0x100
	s_addc_u32 s27, s27, 0
	s_add_u32 s50, s50, 0x100
	s_addc_u32 s51, s51, 0
	s_cmp_gt_u32 s52, 29
	s_cbranch_scc0 .LBB0_833
	s_and_b64 vcc, exec, s[16:17]
	s_cbranch_vccz .LBB0_836
	s_barrier
	s_setprio 1

; #define PG8_STAGE(bufoff, gbase, voff) do { _Pragma("unroll") for (int _i = 0; _i < 2; ++_i) \
;         __builtin_amdgcn_global_load_lds((const unsigned*)((const char*)(gbase) + (voff)[_i]), (LAS unsigned*)(lds + (bufoff) + ldsw + _i * 8192), 16, 0, 0); } while (0)
; #define PG8_LDA(dst, b, h) do { _Pragma("unroll") for (int m = 0; m < 4; ++m) _Pragma("unroll") for (int k = 0; k < 2; ++k) dst[m][k] = *(const LAS bf16x8*)(lds + PG8_SA(b, h) + aoff + m * 2048 + k * 1024); } while (0)
; #define PG8_LDB(dst, b, h) do { _Pragma("unroll") for (int n = 0; n < 2; ++n) _Pragma("unroll") for (int k = 0; k < 2; ++k) dst[n][k] = *(const LAS bf16x8*)(lds + PG8_SB(b, h) + boff + n * 2048 + k * 1024); } while (0)
; #define PG8_MMA(ai, bj, At, Bt) do { __builtin_amdgcn_s_setprio(1); _Pragma("unroll") for (int m = 0; m < 4; ++m) _Pragma("unroll") for (int n = 0; n < 2; ++n) _Pragma("unroll") for (int k = 0; k < 2; ++k) \
;         acc[ai][bj][m][n] = __builtin_amdgcn_mfma_f32_16x16x32_bf16(Bt[n][k], At[m][k], acc[ai][bj][m][n], 0, 0, 0); __builtin_amdgcn_s_setprio(0); } while (0)
; template <class Epi, class Sched, bool ALIGN_EPI = false, bool SP2 = false>
; __device__ __forceinline__ void gemm_phase(LAS unsigned char* lds, const Gemm g, const Sched& S, const Epi& E) {
;     ...
;         const char* nA = has_next ? (const char*)g.A + (size_t)nxt.pm * tstep : cA; const char* nB = has_next ? (const char*)g.Bt + (size_t)nxt.pn * tstep : cB;
;         for (int t = 0; t < nt; t += 2) {
;             const bool last = (t == nt - 2);
;             const char* a1 = cA + (size_t)(t + 1) * kstep;
;             const char* a2 = last ? nA : cA + (size_t)(t + 2) * kstep; const char* b2 = last ? nB : cB + (size_t)(t + 2) * kstep;
;             const char* a3 = a2 + kstep; const char* b3 = b2 + kstep;
;             if (last && has_next) S.a_ready(nxt);
;             if constexpr (SP2) {
;             PG8_LDB(B0, 0, 0); PG8_LDB(B1, 0, 1); PG8_SCHED; PG8_LDA(At, 0, 0); PG8_STAGE(PG8_SA(1, 1), a1 + hstep, voffA);
;             PG8_WAIT_V(8); PG8_WAIT_L(0); PG8_BAR; PG8_MMA(0, 0, At, B0); PG8_MMA(0, 1, At, B1); PG8_BAR; PG8_SCHED;
;             PG8_LDA(At, 0, 1); PG8_STAGE(PG8_SB(0, 0), b2, voffB); PG8_STAGE(PG8_SB(0, 1), b2 + hstep, voffB); PG8_STAGE(PG8_SA(0, 0), a2, voffA);
;             PG8_WAIT_V(8); PG8_WAIT_L(0); PG8_BAR; PG8_MMA(1, 0, At, B0); PG8_MMA(1, 1, At, B1); PG8_BAR; PG8_SCHED;
.LBB0_924:
	s_add_u32 s28, s26, 0xfff80080
	s_addc_u32 s29, s27, -1
	s_add_i32 s51, 0, 0x10000
	s_cmp_eq_u32 s50, 28
	s_cselect_b32 s31, s7, s29
	s_cselect_b32 s30, s8, s28
	v_add_u32_e32 v148, s51, v151
	s_cselect_b32 s29, s19, s49
	s_cselect_b32 s28, s21, s35
	s_add_i32 s54, 0, 0x14000
	ds_read_b128 v[140:143], v148
	ds_read_b128 v[144:147], v148 offset:1024
	ds_read_b128 v[156:159], v148 offset:2048
	ds_read_b128 v[160:163], v148 offset:3072
	v_add_u32_e32 v148, s54, v151
	ds_read_b128 v[164:167], v148
	ds_read_b128 v[168:171], v148 offset:1024
	ds_read_b128 v[172:175], v148 offset:2048
	ds_read_b128 v[176:179], v148 offset:3072
	v_lshl_add_u64 v[212:213], s[26:27], 0, v[136:137]
	s_add_i32 m0, s42, 0xc000
	ds_read_b128 v[180:183], v155
	ds_read_b128 v[184:187], v155 offset:1024
	ds_read_b128 v[188:191], v155 offset:2048
	ds_read_b128 v[192:195], v155 offset:3072
	ds_read_b128 v[196:199], v155 offset:4096
	ds_read_b128 v[200:203], v155 offset:5120
	ds_read_b128 v[204:207], v155 offset:6144
	ds_read_b128 v[208:211], v155 offset:7168
	global_load_lds_dwordx4 v[212:213], off
	v_lshl_add_u64 v[212:213], s[26:27], 0, v[138:139]
	s_add_i32 m0, s42, 0xe000
	s_nop 0
	global_load_lds_dwordx4 v[212:213], off
	s_waitcnt vmcnt(8)
	s_waitcnt lgkmcnt(0)
	s_setprio 1
	s_barrier
	v_mfma_f32_16x16x32_bf16 v[126:129], v[140:143], v[180:183], v[126:129]
	v_mfma_f32_16x16x32_bf16 v[126:129], v[144:147], v[184:187], v[126:129]
	v_mfma_f32_16x16x32_bf16 v[122:125], v[156:159], v[180:183], v[122:125]
	v_mfma_f32_16x16x32_bf16 v[122:125], v[160:163], v[184:187], v[122:125]
	v_mfma_f32_16x16x32_bf16 v[106:109], v[156:159], v[188:191], v[106:109]
	v_mfma_f32_16x16x32_bf16 v[106:109], v[160:163], v[192:195], v[106:109]
	v_mfma_f32_16x16x32_bf16 v[110:113], v[140:143], v[188:191], v[110:113]
	v_mfma_f32_16x16x32_bf16 v[110:113], v[144:147], v[192:195], v[110:113]
	v_mfma_f32_16x16x32_bf16 v[94:97], v[140:143], v[196:199], v[94:97]
	v_mfma_f32_16x16x32_bf16 v[94:97], v[144:147], v[200:203], v[94:97]
	v_mfma_f32_16x16x32_bf16 v[90:93], v[156:159], v[196:199], v[90:93]
	v_mfma_f32_16x16x32_bf16 v[90:93], v[160:163], v[200:203], v[90:93]
	v_mfma_f32_16x16x32_bf16 v[74:77], v[156:159], v[204:207], v[74:77]
	v_mfma_f32_16x16x32_bf16 v[74:77], v[160:163], v[208:211], v[74:77]
	v_mfma_f32_16x16x32_bf16 v[78:81], v[140:143], v[204:207], v[78:81]
	v_mfma_f32_16x16x32_bf16 v[78:81], v[144:147], v[208:211], v[78:81]
	v_mfma_f32_16x16x32_bf16 v[118:121], v[164:167], v[180:183], v[118:121]
	v_mfma_f32_16x16x32_bf16 v[118:121], v[168:171], v[184:187], v[118:121]
	v_mfma_f32_16x16x32_bf16 v[114:117], v[172:175], v[180:183], v[114:117]
	v_mfma_f32_16x16x32_bf16 v[114:117], v[176:179], v[184:187], v[114:117]
	v_mfma_f32_16x16x32_bf16 v[98:101], v[172:175], v[188:191], v[98:101]
	v_mfma_f32_16x16x32_bf16 v[98:101], v[176:179], v[192:195], v[98:101]
	v_mfma_f32_16x16x32_bf16 v[102:105], v[164:167], v[188:191], v[102:105]
	v_mfma_f32_16x16x32_bf16 v[102:105], v[168:171], v[192:195], v[102:105]
	v_mfma_f32_16x16x32_bf16 v[86:89], v[164:167], v[196:199], v[86:89]
	v_mfma_f32_16x16x32_bf16 v[86:89], v[168:171], v[200:203], v[86:89]
	v_mfma_f32_16x16x32_bf16 v[82:85], v[172:175], v[196:199], v[82:85]
	v_mfma_f32_16x16x32_bf16 v[82:85], v[176:179], v[200:203], v[82:85]
	v_mfma_f32_16x16x32_bf16 v[66:69], v[172:175], v[204:207], v[66:69]
	v_mfma_f32_16x16x32_bf16 v[66:69], v[176:179], v[208:211], v[66:69]
	v_mfma_f32_16x16x32_bf16 v[70:73], v[164:167], v[204:207], v[70:73]
	v_mfma_f32_16x16x32_bf16 v[70:73], v[168:171], v[208:211], v[70:73]
	s_barrier
	s_setprio 0
	s_add_i32 s51, s51, s41
	v_lshl_add_u64 v[212:213], s[28:29], 0, v[0:1]
	s_mov_b32 m0, s51
	ds_read_b128 v[180:183], v155 offset:16384
	ds_read_b128 v[184:187], v155 offset:17408
	ds_read_b128 v[188:191], v155 offset:18432
	ds_read_b128 v[192:195], v155 offset:19456
	ds_read_b128 v[196:199], v155 offset:20480
	ds_read_b128 v[200:203], v155 offset:21504
	ds_read_b128 v[204:207], v155 offset:22528
	ds_read_b128 v[208:211], v155 offset:23552
	global_load_lds_dwordx4 v[212:213], off
	s_add_i32 m0, s51, 0x2000
	s_add_u32 s52, s28, 0x80000
	v_lshl_add_u64 v[214:215], s[28:29], 0, v[130:131]
	s_addc_u32 s53, s29, 0
	s_add_i32 s51, s54, s41
	global_load_lds_dwordx4 v[214:215], off
	v_lshl_add_u64 v[216:217], s[52:53], 0, v[0:1]
	s_mov_b32 m0, s51
	v_lshl_add_u64 v[218:219], s[30:31], 0, v[132:133]
	global_load_lds_dwordx4 v[216:217], off
	v_lshl_add_u64 v[216:217], s[52:53], 0, v[130:131]
	s_add_i32 m0, s51, 0x2000
	s_nop 0
	global_load_lds_dwordx4 v[216:217], off
	v_lshl_add_u64 v[216:217], s[30:31], 0, v[134:135]
	s_mov_b32 m0, s42
	s_nop 0
	global_load_lds_dwordx4 v[216:217], off
	s_mov_b32 m0, s43
	s_nop 0
	global_load_lds_dwordx4 v[218:219], off
	s_waitcnt vmcnt(8)
	s_waitcnt lgkmcnt(0)
	s_setprio 1
	s_barrier
; #define PG8_STAGE(bufoff, gbase, voff) do { _Pragma("unroll") for (int _i = 0; _i < 2; ++_i) \
;         __builtin_amdgcn_global_load_lds((const unsigned*)((const char*)(gbase) + (voff)[_i]), (LAS unsigned*)(lds + (bufoff) + ldsw + _i * 8192), 16, 0, 0); } while (0)
; #define PG8_LDA(dst, b, h) do { _Pragma("unroll") for (int m = 0; m < 4; ++m) _Pragma("unroll") for (int k = 0; k < 2; ++k) dst[m][k] = *(const LAS bf16x8*)(lds + PG8_SA(b, h) + aoff + m * 2048 + k * 1024); } while (0)
; #define PG8_LDB(dst, b, h) do { _Pragma("unroll") for (int n = 0; n < 2; ++n) _Pragma("unroll") for (int k = 0; k < 2; ++k) dst[n][k] = *(const LAS bf16x8*)(lds + PG8_SB(b, h) + boff + n * 2048 + k * 1024); } while (0)
; #define PG8_MMA(ai, bj, At, Bt) do { __builtin_amdgcn_s_setprio(1); _Pragma("unroll") for (int m = 0; m < 4; ++m) _Pragma("unroll") for (int n = 0; n < 2; ++n) _Pragma("unroll") for (int k = 0; k < 2; ++k) \
;         acc[ai][bj][m][n] = __builtin_amdgcn_mfma_f32_16x16x32_bf16(Bt[n][k], At[m][k], acc[ai][bj][m][n], 0, 0, 0); __builtin_amdgcn_s_setprio(0); } while (0)
; #define PG8_WAIT_V(n) asm volatile("s_waitcnt vmcnt(" #n ")" ::: "memory")
; #define PG8_WAIT_L(n) asm volatile("s_waitcnt lgkmcnt(" #n ")" ::: "memory")
; #define PG8_BAR __builtin_amdgcn_s_barrier()
; #define PG8_SCHED __builtin_amdgcn_sched_barrier(0)
; template <class Epi, class Sched, bool ALIGN_EPI = false, bool SP2 = false>
; __device__ __forceinline__ void gemm_phase(LAS unsigned char* lds, const Gemm g, const Sched& S, const Epi& E) {
;     ...
;             PG8_WAIT_V(8); PG8_WAIT_L(0); PG8_BAR; PG8_MMA(1, 0, At, B0); PG8_MMA(1, 1, At, B1); PG8_BAR; PG8_SCHED;
;             PG8_LDB(B0, 1, 0); PG8_LDB(B1, 1, 1); PG8_SCHED; PG8_LDA(At, 1, 0); PG8_STAGE(PG8_SA(0, 1), a2 + hstep, voffA);
;             PG8_WAIT_V(8); PG8_WAIT_L(0); PG8_BAR; PG8_MMA(0, 0, At, B0); PG8_MMA(0, 1, At, B1); PG8_BAR; PG8_SCHED;
	v_mfma_f32_16x16x32_bf16 v[62:65], v[140:143], v[180:183], v[62:65]
	v_mfma_f32_16x16x32_bf16 v[62:65], v[144:147], v[184:187], v[62:65]
	v_mfma_f32_16x16x32_bf16 v[58:61], v[156:159], v[180:183], v[58:61]
	v_mfma_f32_16x16x32_bf16 v[58:61], v[160:163], v[184:187], v[58:61]
	v_mfma_f32_16x16x32_bf16 v[42:45], v[156:159], v[188:191], v[42:45]
	v_mfma_f32_16x16x32_bf16 v[42:45], v[160:163], v[192:195], v[42:45]
	v_mfma_f32_16x16x32_bf16 v[46:49], v[140:143], v[188:191], v[46:49]
	v_mfma_f32_16x16x32_bf16 v[46:49], v[144:147], v[192:195], v[46:49]
	v_mfma_f32_16x16x32_bf16 v[30:33], v[140:143], v[196:199], v[30:33]
	v_mfma_f32_16x16x32_bf16 v[30:33], v[144:147], v[200:203], v[30:33]
	v_mfma_f32_16x16x32_bf16 v[26:29], v[156:159], v[196:199], v[26:29]
	v_mfma_f32_16x16x32_bf16 v[26:29], v[160:163], v[200:203], v[26:29]
	v_mfma_f32_16x16x32_bf16 v[10:13], v[156:159], v[204:207], v[10:13]
	v_mfma_f32_16x16x32_bf16 v[10:13], v[160:163], v[208:211], v[10:13]
	v_mfma_f32_16x16x32_bf16 v[14:17], v[140:143], v[204:207], v[14:17]
	v_mfma_f32_16x16x32_bf16 v[14:17], v[144:147], v[208:211], v[14:17]
	v_mfma_f32_16x16x32_bf16 v[54:57], v[164:167], v[180:183], v[54:57]
	v_mfma_f32_16x16x32_bf16 v[54:57], v[168:171], v[184:187], v[54:57]
	v_mfma_f32_16x16x32_bf16 v[50:53], v[172:175], v[180:183], v[50:53]
	v_mfma_f32_16x16x32_bf16 v[50:53], v[176:179], v[184:187], v[50:53]
	v_mfma_f32_16x16x32_bf16 v[34:37], v[172:175], v[188:191], v[34:37]
	v_mfma_f32_16x16x32_bf16 v[34:37], v[176:179], v[192:195], v[34:37]
	v_mfma_f32_16x16x32_bf16 v[38:41], v[164:167], v[188:191], v[38:41]
	v_mfma_f32_16x16x32_bf16 v[38:41], v[168:171], v[192:195], v[38:41]
	v_mfma_f32_16x16x32_bf16 v[22:25], v[164:167], v[196:199], v[22:25]
	v_mfma_f32_16x16x32_bf16 v[22:25], v[168:171], v[200:203], v[22:25]
	v_mfma_f32_16x16x32_bf16 v[18:21], v[172:175], v[196:199], v[18:21]
	v_mfma_f32_16x16x32_bf16 v[18:21], v[176:179], v[200:203], v[18:21]
	v_mfma_f32_16x16x32_bf16 v[2:5], v[172:175], v[204:207], v[2:5]
	v_mfma_f32_16x16x32_bf16 v[2:5], v[176:179], v[208:211], v[2:5]
	v_mfma_f32_16x16x32_bf16 v[6:9], v[164:167], v[204:207], v[6:9]
	v_mfma_f32_16x16x32_bf16 v[6:9], v[168:171], v[208:211], v[6:9]
	s_barrier
	s_setprio 0
	s_add_i32 s51, 0, 0x18000
	v_add_u32_e32 v148, s51, v151
	s_add_i32 s52, 0, 0x1c000
	ds_read_b128 v[140:143], v148
	ds_read_b128 v[144:147], v148 offset:1024
	ds_read_b128 v[156:159], v148 offset:2048
	ds_read_b128 v[160:163], v148 offset:3072
	v_add_u32_e32 v148, s52, v151
	ds_read_b128 v[164:167], v148
	ds_read_b128 v[168:171], v148 offset:1024
	ds_read_b128 v[172:175], v148 offset:2048
	ds_read_b128 v[176:179], v148 offset:3072
	s_add_u32 s30, s30, 0x80000
	s_addc_u32 s31, s31, 0
	s_mov_b32 m0, s44
	v_lshl_add_u64 v[220:221], s[30:31], 0, v[134:135]
	ds_read_b128 v[180:183], v155 offset:32768
	ds_read_b128 v[184:187], v155 offset:33792
	ds_read_b128 v[188:191], v155 offset:34816
	ds_read_b128 v[192:195], v155 offset:35840
	ds_read_b128 v[196:199], v155 offset:36864
	ds_read_b128 v[200:203], v155 offset:37888
	ds_read_b128 v[204:207], v155 offset:38912
	ds_read_b128 v[208:211], v155 offset:39936
	global_load_lds_dwordx4 v[220:221], off
	v_lshl_add_u64 v[220:221], s[30:31], 0, v[132:133]
	s_mov_b32 m0, s45
	s_nop 0
	global_load_lds_dwordx4 v[220:221], off
	s_waitcnt vmcnt(8)
	s_waitcnt lgkmcnt(0)
	s_setprio 1
	s_barrier
	v_mfma_f32_16x16x32_bf16 v[126:129], v[140:143], v[180:183], v[126:129]
	v_mfma_f32_16x16x32_bf16 v[126:129], v[144:147], v[184:187], v[126:129]
	v_mfma_f32_16x16x32_bf16 v[122:125], v[156:159], v[180:183], v[122:125]
	v_mfma_f32_16x16x32_bf16 v[122:125], v[160:163], v[184:187], v[122:125]
	v_mfma_f32_16x16x32_bf16 v[106:109], v[156:159], v[188:191], v[106:109]
	v_mfma_f32_16x16x32_bf16 v[106:109], v[160:163], v[192:195], v[106:109]
	v_mfma_f32_16x16x32_bf16 v[110:113], v[140:143], v[188:191], v[110:113]
	v_mfma_f32_16x16x32_bf16 v[110:113], v[144:147], v[192:195], v[110:113]
	v_mfma_f32_16x16x32_bf16 v[94:97], v[140:143], v[196:199], v[94:97]
	v_mfma_f32_16x16x32_bf16 v[94:97], v[144:147], v[200:203], v[94:97]
	v_mfma_f32_16x16x32_bf16 v[90:93], v[156:159], v[196:199], v[90:93]
	v_mfma_f32_16x16x32_bf16 v[90:93], v[160:163], v[200:203], v[90:93]
	v_mfma_f32_16x16x32_bf16 v[74:77], v[156:159], v[204:207], v[74:77]
	v_mfma_f32_16x16x32_bf16 v[74:77], v[160:163], v[208:211], v[74:77]
	v_mfma_f32_16x16x32_bf16 v[78:81], v[140:143], v[204:207], v[78:81]
	v_mfma_f32_16x16x32_bf16 v[78:81], v[144:147], v[208:211], v[78:81]
	v_mfma_f32_16x16x32_bf16 v[118:121], v[164:167], v[180:183], v[118:121]
	v_mfma_f32_16x16x32_bf16 v[118:121], v[168:171], v[184:187], v[118:121]
	v_mfma_f32_16x16x32_bf16 v[114:117], v[172:175], v[180:183], v[114:117]
	v_mfma_f32_16x16x32_bf16 v[114:117], v[176:179], v[184:187], v[114:117]
	v_mfma_f32_16x16x32_bf16 v[98:101], v[172:175], v[188:191], v[98:101]
	v_mfma_f32_16x16x32_bf16 v[98:101], v[176:179], v[192:195], v[98:101]
	v_mfma_f32_16x16x32_bf16 v[102:105], v[164:167], v[188:191], v[102:105]
	v_mfma_f32_16x16x32_bf16 v[102:105], v[168:171], v[192:195], v[102:105]
	v_mfma_f32_16x16x32_bf16 v[86:89], v[164:167], v[196:199], v[86:89]
	v_mfma_f32_16x16x32_bf16 v[86:89], v[168:171], v[200:203], v[86:89]
	v_mfma_f32_16x16x32_bf16 v[82:85], v[172:175], v[196:199], v[82:85]
	v_mfma_f32_16x16x32_bf16 v[82:85], v[176:179], v[200:203], v[82:85]
	v_mfma_f32_16x16x32_bf16 v[66:69], v[172:175], v[204:207], v[66:69]
	v_mfma_f32_16x16x32_bf16 v[66:69], v[176:179], v[208:211], v[66:69]
	v_mfma_f32_16x16x32_bf16 v[70:73], v[164:167], v[204:207], v[70:73]
	v_mfma_f32_16x16x32_bf16 v[70:73], v[168:171], v[208:211], v[70:73]
	s_barrier
; #define PG8_STAGE(bufoff, gbase, voff) do { _Pragma("unroll") for (int _i = 0; _i < 2; ++_i) \
;         __builtin_amdgcn_global_load_lds((const unsigned*)((const char*)(gbase) + (voff)[_i]), (LAS unsigned*)(lds + (bufoff) + ldsw + _i * 8192), 16, 0, 0); } while (0)
; #define PG8_LDA(dst, b, h) do { _Pragma("unroll") for (int m = 0; m < 4; ++m) _Pragma("unroll") for (int k = 0; k < 2; ++k) dst[m][k] = *(const LAS bf16x8*)(lds + PG8_SA(b, h) + aoff + m * 2048 + k * 1024); } while (0)
; #define PG8_MMA(ai, bj, At, Bt) do { __builtin_amdgcn_s_setprio(1); _Pragma("unroll") for (int m = 0; m < 4; ++m) _Pragma("unroll") for (int n = 0; n < 2; ++n) _Pragma("unroll") for (int k = 0; k < 2; ++k) \
;         acc[ai][bj][m][n] = __builtin_amdgcn_mfma_f32_16x16x32_bf16(Bt[n][k], At[m][k], acc[ai][bj][m][n], 0, 0, 0); __builtin_amdgcn_s_setprio(0); } while (0)
; #define PG8_WAIT_V(n) asm volatile("s_waitcnt vmcnt(" #n ")" ::: "memory")
; #define PG8_WAIT_L(n) asm volatile("s_waitcnt lgkmcnt(" #n ")" ::: "memory")
; #define PG8_BAR __builtin_amdgcn_s_barrier()
; #define PG8_SCHED __builtin_amdgcn_sched_barrier(0)
; template <class Epi, class Sched, bool ALIGN_EPI = false, bool SP2 = false>
; __device__ __forceinline__ void gemm_phase(LAS unsigned char* lds, const Gemm g, const Sched& S, const Epi& E) {
;     ...
;             PG8_LDA(At, 1, 1); PG8_STAGE(PG8_SB(1, 0), b3, voffB); PG8_STAGE(PG8_SB(1, 1), b3 + hstep, voffB); PG8_STAGE(PG8_SA(1, 0), a3, voffA);
;             PG8_WAIT_V(8); PG8_WAIT_L(0); PG8_BAR; PG8_MMA(1, 0, At, B0); PG8_MMA(1, 1, At, B1); PG8_BAR; PG8_SCHED;
;     ...
;         if constexpr (ALIGN_EPI) { if (wr == 0) PG8_BAR; }
	s_setprio 0
	s_add_i32 s30, s51, s41
	v_lshl_add_u64 v[212:213], v[212:213], 0, s[12:13]
	s_mov_b32 m0, s30
	ds_read_b128 v[180:183], v155 offset:49152
	ds_read_b128 v[184:187], v155 offset:50176
	ds_read_b128 v[188:191], v155 offset:51200
	ds_read_b128 v[192:195], v155 offset:52224
	ds_read_b128 v[196:199], v155 offset:53248
	ds_read_b128 v[200:203], v155 offset:54272
	ds_read_b128 v[204:207], v155 offset:55296
	ds_read_b128 v[208:211], v155 offset:56320
	global_load_lds_dwordx4 v[212:213], off
	s_add_i32 m0, s30, 0x2000
	s_add_u32 s28, s28, 0x80080
	v_lshl_add_u64 v[212:213], v[214:215], 0, s[12:13]
	s_addc_u32 s29, s29, 0
	s_add_i32 s30, s52, s41
	global_load_lds_dwordx4 v[212:213], off
	v_lshl_add_u64 v[212:213], s[28:29], 0, v[0:1]
	s_mov_b32 m0, s30
	s_nop 0
	global_load_lds_dwordx4 v[212:213], off
	v_lshl_add_u64 v[212:213], s[28:29], 0, v[130:131]
	s_add_i32 m0, s30, 0x2000
	s_nop 0
	global_load_lds_dwordx4 v[212:213], off
	v_lshl_add_u64 v[212:213], v[216:217], 0, s[12:13]
	s_mov_b32 m0, s46
	s_nop 0
	global_load_lds_dwordx4 v[212:213], off
	v_lshl_add_u64 v[212:213], v[218:219], 0, s[12:13]
	s_mov_b32 m0, s47
	s_nop 0
	global_load_lds_dwordx4 v[212:213], off
	s_waitcnt vmcnt(8)
	s_waitcnt lgkmcnt(0)
	s_setprio 1
	s_barrier
	v_mfma_f32_16x16x32_bf16 v[62:65], v[140:143], v[180:183], v[62:65]
	v_mfma_f32_16x16x32_bf16 v[62:65], v[144:147], v[184:187], v[62:65]
	v_mfma_f32_16x16x32_bf16 v[58:61], v[156:159], v[180:183], v[58:61]
	v_mfma_f32_16x16x32_bf16 v[58:61], v[160:163], v[184:187], v[58:61]
	v_mfma_f32_16x16x32_bf16 v[42:45], v[156:159], v[188:191], v[42:45]
	v_mfma_f32_16x16x32_bf16 v[42:45], v[160:163], v[192:195], v[42:45]
	v_mfma_f32_16x16x32_bf16 v[46:49], v[140:143], v[188:191], v[46:49]
	v_mfma_f32_16x16x32_bf16 v[46:49], v[144:147], v[192:195], v[46:49]
	v_mfma_f32_16x16x32_bf16 v[30:33], v[140:143], v[196:199], v[30:33]
	v_mfma_f32_16x16x32_bf16 v[30:33], v[144:147], v[200:203], v[30:33]
	v_mfma_f32_16x16x32_bf16 v[26:29], v[156:159], v[196:199], v[26:29]
	v_mfma_f32_16x16x32_bf16 v[26:29], v[160:163], v[200:203], v[26:29]
	v_mfma_f32_16x16x32_bf16 v[10:13], v[156:159], v[204:207], v[10:13]
	v_mfma_f32_16x16x32_bf16 v[10:13], v[160:163], v[208:211], v[10:13]
	v_mfma_f32_16x16x32_bf16 v[14:17], v[140:143], v[204:207], v[14:17]
	v_mfma_f32_16x16x32_bf16 v[14:17], v[144:147], v[208:211], v[14:17]
	v_mfma_f32_16x16x32_bf16 v[54:57], v[164:167], v[180:183], v[54:57]
	v_mfma_f32_16x16x32_bf16 v[54:57], v[168:171], v[184:187], v[54:57]
	v_mfma_f32_16x16x32_bf16 v[50:53], v[172:175], v[180:183], v[50:53]
	v_mfma_f32_16x16x32_bf16 v[50:53], v[176:179], v[184:187], v[50:53]
	v_mfma_f32_16x16x32_bf16 v[34:37], v[172:175], v[188:191], v[34:37]
	v_mfma_f32_16x16x32_bf16 v[34:37], v[176:179], v[192:195], v[34:37]
	v_mfma_f32_16x16x32_bf16 v[38:41], v[164:167], v[188:191], v[38:41]
	v_mfma_f32_16x16x32_bf16 v[38:41], v[168:171], v[192:195], v[38:41]
	v_mfma_f32_16x16x32_bf16 v[22:25], v[164:167], v[196:199], v[22:25]
	v_mfma_f32_16x16x32_bf16 v[22:25], v[168:171], v[200:203], v[22:25]
	v_mfma_f32_16x16x32_bf16 v[18:21], v[172:175], v[196:199], v[18:21]
	v_mfma_f32_16x16x32_bf16 v[18:21], v[176:179], v[200:203], v[18:21]
	v_mfma_f32_16x16x32_bf16 v[2:5], v[172:175], v[204:207], v[2:5]
	v_mfma_f32_16x16x32_bf16 v[2:5], v[176:179], v[208:211], v[2:5]
	v_mfma_f32_16x16x32_bf16 v[6:9], v[164:167], v[204:207], v[6:9]
	v_mfma_f32_16x16x32_bf16 v[6:9], v[168:171], v[208:211], v[6:9]
	s_barrier
	s_setprio 0
	s_add_i32 s50, s50, 2
	s_add_u32 s26, s26, 0x100
	s_addc_u32 s27, s27, 0
	s_add_u32 s35, s35, 0x100
	s_addc_u32 s49, s49, 0
	s_cmp_gt_u32 s50, 29
	s_cbranch_scc0 .LBB0_924
	s_and_b64 vcc, exec, s[16:17]
	s_cbranch_vccz .LBB0_927
	s_barrier
	s_setprio 1

; #define PG8_STAGE(bufoff, gbase, voff) do { _Pragma("unroll") for (int _i = 0; _i < 2; ++_i) \
;         __builtin_amdgcn_global_load_lds((const unsigned*)((const char*)(gbase) + (voff)[_i]), (LAS unsigned*)(lds + (bufoff) + ldsw + _i * 8192), 16, 0, 0); } while (0)
; #define PG8_LDA(dst, b, h) do { _Pragma("unroll") for (int m = 0; m < 4; ++m) _Pragma("unroll") for (int k = 0; k < 2; ++k) dst[m][k] = *(const LAS bf16x8*)(lds + PG8_SA(b, h) + aoff + m * 2048 + k * 1024); } while (0)
; #define PG8_LDB(dst, b, h) do { _Pragma("unroll") for (int n = 0; n < 2; ++n) _Pragma("unroll") for (int k = 0; k < 2; ++k) dst[n][k] = *(const LAS bf16x8*)(lds + PG8_SB(b, h) + boff + n * 2048 + k * 1024); } while (0)
; #define PG8_MMA(ai, bj, At, Bt) do { __builtin_amdgcn_s_setprio(1); _Pragma("unroll") for (int m = 0; m < 4; ++m) _Pragma("unroll") for (int n = 0; n < 2; ++n) _Pragma("unroll") for (int k = 0; k < 2; ++k) \
;         acc[ai][bj][m][n] = __builtin_amdgcn_mfma_f32_16x16x32_bf16(Bt[n][k], At[m][k], acc[ai][bj][m][n], 0, 0, 0); __builtin_amdgcn_s_setprio(0); } while (0)
; template <class Epi, class Sched, bool ALIGN_EPI = false, bool SP2 = false>
; __device__ __forceinline__ void gemm_phase(LAS unsigned char* lds, const Gemm g, const Sched& S, const Epi& E) {
;     ...
;         const char* nA = has_next ? (const char*)g.A + (size_t)nxt.pm * tstep : cA; const char* nB = has_next ? (const char*)g.Bt + (size_t)nxt.pn * tstep : cB;
;         for (int t = 0; t < nt; t += 2) {
;             const bool last = (t == nt - 2);
;             const char* a1 = cA + (size_t)(t + 1) * kstep;
;             const char* a2 = last ? nA : cA + (size_t)(t + 2) * kstep; const char* b2 = last ? nB : cB + (size_t)(t + 2) * kstep;
;             const char* a3 = a2 + kstep; const char* b3 = b2 + kstep;
;             if (last && has_next) S.a_ready(nxt);
;             if constexpr (SP2) {
;             PG8_LDB(B0, 0, 0); PG8_LDB(B1, 0, 1); PG8_SCHED; PG8_LDA(At, 0, 0); PG8_STAGE(PG8_SA(1, 1), a1 + hstep, voffA);
;             PG8_WAIT_V(8); PG8_WAIT_L(0); PG8_BAR; PG8_MMA(0, 0, At, B0); PG8_MMA(0, 1, At, B1); PG8_BAR; PG8_SCHED;
;             PG8_LDA(At, 0, 1); PG8_STAGE(PG8_SB(0, 0), b2, voffB); PG8_STAGE(PG8_SB(0, 1), b2 + hstep, voffB); PG8_STAGE(PG8_SA(0, 0), a2, voffA);
;             PG8_WAIT_V(8); PG8_WAIT_L(0); PG8_BAR; PG8_MMA(1, 0, At, B0); PG8_MMA(1, 1, At, B1); PG8_BAR; PG8_SCHED;
.LBB0_1007:
	s_add_u32 s24, s22, 0x100
	s_addc_u32 s25, s23, 0
	s_add_i32 s49, 0, 0x10000
	s_cmpk_eq_i32 s48, 0x54
	s_cselect_b32 s29, s1, s25
	s_cselect_b32 s28, s0, s24
	s_cselect_b32 s27, s21, s47
	s_cselect_b32 s26, s20, s46
	s_add_i32 s50, 0, 0x14000
	v_add_u32_e32 v126, s49, v247
	v_add_u32_e32 v158, s50, v247
	ds_read_b128 v[90:93], v126
	ds_read_b128 v[102:105], v126 offset:1024
	ds_read_b128 v[114:117], v126 offset:2048
	ds_read_b128 v[126:129], v126 offset:3072
	ds_read_b128 v[138:141], v158
	ds_read_b128 v[142:145], v158 offset:1024
	ds_read_b128 v[154:157], v158 offset:2048
	ds_read_b128 v[158:161], v158 offset:3072
	v_lshl_add_u64 v[204:205], s[22:23], 0, v[200:201]
	s_add_i32 m0, s8, 0xc000
	ds_read_b128 v[162:165], v249
	ds_read_b128 v[166:169], v249 offset:1024
	ds_read_b128 v[170:173], v249 offset:2048
	ds_read_b128 v[174:177], v249 offset:3072
	ds_read_b128 v[178:181], v249 offset:4096
	ds_read_b128 v[182:185], v249 offset:5120
	ds_read_b128 v[186:189], v249 offset:6144
	ds_read_b128 v[190:193], v249 offset:7168
	global_load_lds_dwordx4 v[204:205], off
	v_lshl_add_u64 v[204:205], s[22:23], 0, v[202:203]
	s_add_i32 m0, s8, 0xe000
	s_nop 0
	global_load_lds_dwordx4 v[204:205], off
	s_waitcnt vmcnt(8)
	s_waitcnt lgkmcnt(0)
	s_setprio 1
	s_barrier
	v_mfma_f32_16x16x32_bf16 v[150:153], v[90:93], v[162:165], v[150:153]
	v_mfma_f32_16x16x32_bf16 v[150:153], v[102:105], v[166:169], v[150:153]
	v_mfma_f32_16x16x32_bf16 v[146:149], v[114:117], v[162:165], v[146:149]
	v_mfma_f32_16x16x32_bf16 v[146:149], v[126:129], v[166:169], v[146:149]
	v_mfma_f32_16x16x32_bf16 v[118:121], v[114:117], v[170:173], v[118:121]
	v_mfma_f32_16x16x32_bf16 v[118:121], v[126:129], v[174:177], v[118:121]
	v_mfma_f32_16x16x32_bf16 v[122:125], v[90:93], v[170:173], v[122:125]
	v_mfma_f32_16x16x32_bf16 v[122:125], v[102:105], v[174:177], v[122:125]
	v_mfma_f32_16x16x32_bf16 v[98:101], v[90:93], v[178:181], v[98:101]
	v_mfma_f32_16x16x32_bf16 v[98:101], v[102:105], v[182:185], v[98:101]
	v_mfma_f32_16x16x32_bf16 v[94:97], v[114:117], v[178:181], v[94:97]
	v_mfma_f32_16x16x32_bf16 v[94:97], v[126:129], v[182:185], v[94:97]
	v_mfma_f32_16x16x32_bf16 v[74:77], v[114:117], v[186:189], v[74:77]
	v_mfma_f32_16x16x32_bf16 v[74:77], v[126:129], v[190:193], v[74:77]
	v_mfma_f32_16x16x32_bf16 v[78:81], v[90:93], v[186:189], v[78:81]
	v_mfma_f32_16x16x32_bf16 v[78:81], v[102:105], v[190:193], v[78:81]
	v_mfma_f32_16x16x32_bf16 v[134:137], v[138:141], v[162:165], v[134:137]
	v_mfma_f32_16x16x32_bf16 v[134:137], v[142:145], v[166:169], v[134:137]
	v_mfma_f32_16x16x32_bf16 v[130:133], v[154:157], v[162:165], v[130:133]
	v_mfma_f32_16x16x32_bf16 v[130:133], v[158:161], v[166:169], v[130:133]
	v_mfma_f32_16x16x32_bf16 v[106:109], v[154:157], v[170:173], v[106:109]
	v_mfma_f32_16x16x32_bf16 v[106:109], v[158:161], v[174:177], v[106:109]
	v_mfma_f32_16x16x32_bf16 v[110:113], v[138:141], v[170:173], v[110:113]
	v_mfma_f32_16x16x32_bf16 v[110:113], v[142:145], v[174:177], v[110:113]
	v_mfma_f32_16x16x32_bf16 v[86:89], v[138:141], v[178:181], v[86:89]
	v_mfma_f32_16x16x32_bf16 v[86:89], v[142:145], v[182:185], v[86:89]
	v_mfma_f32_16x16x32_bf16 v[82:85], v[154:157], v[178:181], v[82:85]
	v_mfma_f32_16x16x32_bf16 v[82:85], v[158:161], v[182:185], v[82:85]
	v_mfma_f32_16x16x32_bf16 v[66:69], v[154:157], v[186:189], v[66:69]
	v_mfma_f32_16x16x32_bf16 v[66:69], v[158:161], v[190:193], v[66:69]
	v_mfma_f32_16x16x32_bf16 v[70:73], v[138:141], v[186:189], v[70:73]
	v_mfma_f32_16x16x32_bf16 v[70:73], v[142:145], v[190:193], v[70:73]
	s_barrier
	s_setprio 0
	s_add_i32 s22, s49, s7
	v_lshl_add_u64 v[204:205], s[26:27], 0, v[0:1]
	s_mov_b32 m0, s22
	ds_read_b128 v[162:165], v249 offset:16384
	ds_read_b128 v[166:169], v249 offset:17408
	ds_read_b128 v[170:173], v249 offset:18432
	ds_read_b128 v[174:177], v249 offset:19456
	ds_read_b128 v[178:181], v249 offset:20480
	ds_read_b128 v[182:185], v249 offset:21504
	ds_read_b128 v[186:189], v249 offset:22528
	ds_read_b128 v[190:193], v249 offset:23552
	global_load_lds_dwordx4 v[204:205], off
	s_add_i32 m0, s22, 0x2000
	s_add_u32 s22, s26, 0x160000
	v_lshl_add_u64 v[206:207], s[26:27], 0, v[194:195]
	s_addc_u32 s23, s27, 0
	s_add_i32 s49, s50, s7
	global_load_lds_dwordx4 v[206:207], off
	v_lshl_add_u64 v[208:209], s[22:23], 0, v[0:1]
	s_mov_b32 m0, s49
	v_lshl_add_u64 v[210:211], s[28:29], 0, v[196:197]
	global_load_lds_dwordx4 v[208:209], off
	v_lshl_add_u64 v[208:209], s[22:23], 0, v[194:195]
	s_add_i32 m0, s49, 0x2000
	s_nop 0
	global_load_lds_dwordx4 v[208:209], off
	v_lshl_add_u64 v[208:209], s[28:29], 0, v[198:199]
	s_mov_b32 m0, s8
	s_nop 0
	global_load_lds_dwordx4 v[208:209], off
	s_mov_b32 m0, s9
	s_nop 0
	global_load_lds_dwordx4 v[210:211], off
	s_waitcnt vmcnt(8)
	s_waitcnt lgkmcnt(0)
	s_setprio 1
	s_barrier
; #define PG8_STAGE(bufoff, gbase, voff) do { _Pragma("unroll") for (int _i = 0; _i < 2; ++_i) \
;         __builtin_amdgcn_global_load_lds((const unsigned*)((const char*)(gbase) + (voff)[_i]), (LAS unsigned*)(lds + (bufoff) + ldsw + _i * 8192), 16, 0, 0); } while (0)
; #define PG8_LDA(dst, b, h) do { _Pragma("unroll") for (int m = 0; m < 4; ++m) _Pragma("unroll") for (int k = 0; k < 2; ++k) dst[m][k] = *(const LAS bf16x8*)(lds + PG8_SA(b, h) + aoff + m * 2048 + k * 1024); } while (0)
; #define PG8_LDB(dst, b, h) do { _Pragma("unroll") for (int n = 0; n < 2; ++n) _Pragma("unroll") for (int k = 0; k < 2; ++k) dst[n][k] = *(const LAS bf16x8*)(lds + PG8_SB(b, h) + boff + n * 2048 + k * 1024); } while (0)
; #define PG8_MMA(ai, bj, At, Bt) do { __builtin_amdgcn_s_setprio(1); _Pragma("unroll") for (int m = 0; m < 4; ++m) _Pragma("unroll") for (int n = 0; n < 2; ++n) _Pragma("unroll") for (int k = 0; k < 2; ++k) \
;         acc[ai][bj][m][n] = __builtin_amdgcn_mfma_f32_16x16x32_bf16(Bt[n][k], At[m][k], acc[ai][bj][m][n], 0, 0, 0); __builtin_amdgcn_s_setprio(0); } while (0)
; #define PG8_WAIT_V(n) asm volatile("s_waitcnt vmcnt(" #n ")" ::: "memory")
; #define PG8_WAIT_L(n) asm volatile("s_waitcnt lgkmcnt(" #n ")" ::: "memory")
; #define PG8_BAR __builtin_amdgcn_s_barrier()
; #define PG8_SCHED __builtin_amdgcn_sched_barrier(0)
; template <class Epi, class Sched, bool ALIGN_EPI = false, bool SP2 = false>
; __device__ __forceinline__ void gemm_phase(LAS unsigned char* lds, const Gemm g, const Sched& S, const Epi& E) {
;     ...
;             PG8_WAIT_V(8); PG8_WAIT_L(0); PG8_BAR; PG8_MMA(1, 0, At, B0); PG8_MMA(1, 1, At, B1); PG8_BAR; PG8_SCHED;
;             PG8_LDB(B0, 1, 0); PG8_LDB(B1, 1, 1); PG8_SCHED; PG8_LDA(At, 1, 0); PG8_STAGE(PG8_SA(0, 1), a2 + hstep, voffA);
;             PG8_WAIT_V(8); PG8_WAIT_L(0); PG8_BAR; PG8_MMA(0, 0, At, B0); PG8_MMA(0, 1, At, B1); PG8_BAR; PG8_SCHED;
	v_mfma_f32_16x16x32_bf16 v[62:65], v[90:93], v[162:165], v[62:65]
	v_mfma_f32_16x16x32_bf16 v[62:65], v[102:105], v[166:169], v[62:65]
	v_mfma_f32_16x16x32_bf16 v[58:61], v[114:117], v[162:165], v[58:61]
	v_mfma_f32_16x16x32_bf16 v[58:61], v[126:129], v[166:169], v[58:61]
	v_mfma_f32_16x16x32_bf16 v[42:45], v[114:117], v[170:173], v[42:45]
	v_mfma_f32_16x16x32_bf16 v[42:45], v[126:129], v[174:177], v[42:45]
	v_mfma_f32_16x16x32_bf16 v[46:49], v[90:93], v[170:173], v[46:49]
	v_mfma_f32_16x16x32_bf16 v[46:49], v[102:105], v[174:177], v[46:49]
	v_mfma_f32_16x16x32_bf16 v[30:33], v[90:93], v[178:181], v[30:33]
	v_mfma_f32_16x16x32_bf16 v[30:33], v[102:105], v[182:185], v[30:33]
	v_mfma_f32_16x16x32_bf16 v[26:29], v[114:117], v[178:181], v[26:29]
	v_mfma_f32_16x16x32_bf16 v[26:29], v[126:129], v[182:185], v[26:29]
	v_mfma_f32_16x16x32_bf16 v[10:13], v[114:117], v[186:189], v[10:13]
	v_mfma_f32_16x16x32_bf16 v[10:13], v[126:129], v[190:193], v[10:13]
	v_mfma_f32_16x16x32_bf16 v[14:17], v[90:93], v[186:189], v[14:17]
	v_mfma_f32_16x16x32_bf16 v[14:17], v[102:105], v[190:193], v[14:17]
	v_mfma_f32_16x16x32_bf16 v[54:57], v[138:141], v[162:165], v[54:57]
	v_mfma_f32_16x16x32_bf16 v[54:57], v[142:145], v[166:169], v[54:57]
	v_mfma_f32_16x16x32_bf16 v[50:53], v[154:157], v[162:165], v[50:53]
	v_mfma_f32_16x16x32_bf16 v[50:53], v[158:161], v[166:169], v[50:53]
	v_mfma_f32_16x16x32_bf16 v[34:37], v[154:157], v[170:173], v[34:37]
	v_mfma_f32_16x16x32_bf16 v[34:37], v[158:161], v[174:177], v[34:37]
	v_mfma_f32_16x16x32_bf16 v[38:41], v[138:141], v[170:173], v[38:41]
	v_mfma_f32_16x16x32_bf16 v[38:41], v[142:145], v[174:177], v[38:41]
	v_mfma_f32_16x16x32_bf16 v[22:25], v[138:141], v[178:181], v[22:25]
	v_mfma_f32_16x16x32_bf16 v[22:25], v[142:145], v[182:185], v[22:25]
	v_mfma_f32_16x16x32_bf16 v[18:21], v[154:157], v[178:181], v[18:21]
	v_mfma_f32_16x16x32_bf16 v[18:21], v[158:161], v[182:185], v[18:21]
	v_mfma_f32_16x16x32_bf16 v[2:5], v[154:157], v[186:189], v[2:5]
	v_mfma_f32_16x16x32_bf16 v[2:5], v[158:161], v[190:193], v[2:5]
	v_mfma_f32_16x16x32_bf16 v[6:9], v[138:141], v[186:189], v[6:9]
	v_mfma_f32_16x16x32_bf16 v[6:9], v[142:145], v[190:193], v[6:9]
	s_barrier
	s_setprio 0
	s_add_i32 s49, 0, 0x18000
	s_add_i32 s50, 0, 0x1c000
	v_add_u32_e32 v126, s49, v247
	v_add_u32_e32 v158, s50, v247
	ds_read_b128 v[90:93], v126
	ds_read_b128 v[102:105], v126 offset:1024
	ds_read_b128 v[114:117], v126 offset:2048
	ds_read_b128 v[126:129], v126 offset:3072
	ds_read_b128 v[138:141], v158
	ds_read_b128 v[142:145], v158 offset:1024
	ds_read_b128 v[154:157], v158 offset:2048
	ds_read_b128 v[158:161], v158 offset:3072
	s_add_u32 s22, s28, 0x160000
	s_addc_u32 s23, s29, 0
	s_mov_b32 m0, s30
	v_lshl_add_u64 v[212:213], s[22:23], 0, v[198:199]
	ds_read_b128 v[162:165], v249 offset:32768
	ds_read_b128 v[166:169], v249 offset:33792
	ds_read_b128 v[170:173], v249 offset:34816
	ds_read_b128 v[174:177], v249 offset:35840
	ds_read_b128 v[178:181], v249 offset:36864
	ds_read_b128 v[182:185], v249 offset:37888
	ds_read_b128 v[186:189], v249 offset:38912
	ds_read_b128 v[190:193], v249 offset:39936
	global_load_lds_dwordx4 v[212:213], off
	v_lshl_add_u64 v[212:213], s[22:23], 0, v[196:197]
	s_mov_b32 m0, s31
	s_nop 0
	global_load_lds_dwordx4 v[212:213], off
	s_waitcnt vmcnt(8)
	s_waitcnt lgkmcnt(0)
	s_setprio 1
	s_barrier
	v_mfma_f32_16x16x32_bf16 v[150:153], v[90:93], v[162:165], v[150:153]
	v_mfma_f32_16x16x32_bf16 v[150:153], v[102:105], v[166:169], v[150:153]
	v_mfma_f32_16x16x32_bf16 v[146:149], v[114:117], v[162:165], v[146:149]
	v_mfma_f32_16x16x32_bf16 v[146:149], v[126:129], v[166:169], v[146:149]
	v_mfma_f32_16x16x32_bf16 v[118:121], v[114:117], v[170:173], v[118:121]
	v_mfma_f32_16x16x32_bf16 v[118:121], v[126:129], v[174:177], v[118:121]
	v_mfma_f32_16x16x32_bf16 v[122:125], v[90:93], v[170:173], v[122:125]
	v_mfma_f32_16x16x32_bf16 v[122:125], v[102:105], v[174:177], v[122:125]
	v_mfma_f32_16x16x32_bf16 v[98:101], v[90:93], v[178:181], v[98:101]
	v_mfma_f32_16x16x32_bf16 v[98:101], v[102:105], v[182:185], v[98:101]
	v_mfma_f32_16x16x32_bf16 v[94:97], v[114:117], v[178:181], v[94:97]
	v_mfma_f32_16x16x32_bf16 v[94:97], v[126:129], v[182:185], v[94:97]
	v_mfma_f32_16x16x32_bf16 v[74:77], v[114:117], v[186:189], v[74:77]
	v_mfma_f32_16x16x32_bf16 v[74:77], v[126:129], v[190:193], v[74:77]
	v_mfma_f32_16x16x32_bf16 v[78:81], v[90:93], v[186:189], v[78:81]
	v_mfma_f32_16x16x32_bf16 v[78:81], v[102:105], v[190:193], v[78:81]
	v_mfma_f32_16x16x32_bf16 v[134:137], v[138:141], v[162:165], v[134:137]
	v_mfma_f32_16x16x32_bf16 v[134:137], v[142:145], v[166:169], v[134:137]
	v_mfma_f32_16x16x32_bf16 v[130:133], v[154:157], v[162:165], v[130:133]
	v_mfma_f32_16x16x32_bf16 v[130:133], v[158:161], v[166:169], v[130:133]
	v_mfma_f32_16x16x32_bf16 v[106:109], v[154:157], v[170:173], v[106:109]
	v_mfma_f32_16x16x32_bf16 v[106:109], v[158:161], v[174:177], v[106:109]
	v_mfma_f32_16x16x32_bf16 v[110:113], v[138:141], v[170:173], v[110:113]
	v_mfma_f32_16x16x32_bf16 v[110:113], v[142:145], v[174:177], v[110:113]
	v_mfma_f32_16x16x32_bf16 v[86:89], v[138:141], v[178:181], v[86:89]
	v_mfma_f32_16x16x32_bf16 v[86:89], v[142:145], v[182:185], v[86:89]
	v_mfma_f32_16x16x32_bf16 v[82:85], v[154:157], v[178:181], v[82:85]
	v_mfma_f32_16x16x32_bf16 v[82:85], v[158:161], v[182:185], v[82:85]
	v_mfma_f32_16x16x32_bf16 v[66:69], v[154:157], v[186:189], v[66:69]
	v_mfma_f32_16x16x32_bf16 v[66:69], v[158:161], v[190:193], v[66:69]
	v_mfma_f32_16x16x32_bf16 v[70:73], v[138:141], v[186:189], v[70:73]
	v_mfma_f32_16x16x32_bf16 v[70:73], v[142:145], v[190:193], v[70:73]
	s_barrier
; #define PG8_STAGE(bufoff, gbase, voff) do { _Pragma("unroll") for (int _i = 0; _i < 2; ++_i) \
;         __builtin_amdgcn_global_load_lds((const unsigned*)((const char*)(gbase) + (voff)[_i]), (LAS unsigned*)(lds + (bufoff) + ldsw + _i * 8192), 16, 0, 0); } while (0)
; #define PG8_LDA(dst, b, h) do { _Pragma("unroll") for (int m = 0; m < 4; ++m) _Pragma("unroll") for (int k = 0; k < 2; ++k) dst[m][k] = *(const LAS bf16x8*)(lds + PG8_SA(b, h) + aoff + m * 2048 + k * 1024); } while (0)
; #define PG8_MMA(ai, bj, At, Bt) do { __builtin_amdgcn_s_setprio(1); _Pragma("unroll") for (int m = 0; m < 4; ++m) _Pragma("unroll") for (int n = 0; n < 2; ++n) _Pragma("unroll") for (int k = 0; k < 2; ++k) \
;         acc[ai][bj][m][n] = __builtin_amdgcn_mfma_f32_16x16x32_bf16(Bt[n][k], At[m][k], acc[ai][bj][m][n], 0, 0, 0); __builtin_amdgcn_s_setprio(0); } while (0)
; #define PG8_WAIT_V(n) asm volatile("s_waitcnt vmcnt(" #n ")" ::: "memory")
; #define PG8_WAIT_L(n) asm volatile("s_waitcnt lgkmcnt(" #n ")" ::: "memory")
; #define PG8_BAR __builtin_amdgcn_s_barrier()
; #define PG8_SCHED __builtin_amdgcn_sched_barrier(0)
; template <class Epi, class Sched, bool ALIGN_EPI = false, bool SP2 = false>
; __device__ __forceinline__ void gemm_phase(LAS unsigned char* lds, const Gemm g, const Sched& S, const Epi& E) {
;     ...
;             PG8_LDA(At, 1, 1); PG8_STAGE(PG8_SB(1, 0), b3, voffB); PG8_STAGE(PG8_SB(1, 1), b3 + hstep, voffB); PG8_STAGE(PG8_SA(1, 0), a3, voffA);
;             PG8_WAIT_V(8); PG8_WAIT_L(0); PG8_BAR; PG8_MMA(1, 0, At, B0); PG8_MMA(1, 1, At, B1); PG8_BAR; PG8_SCHED;
;     ...
;         if constexpr (ALIGN_EPI) { if (wr == 0) PG8_BAR; }
	s_setprio 0
	s_add_i32 s22, s49, s7
	v_lshl_add_u64 v[204:205], v[204:205], 0, s[12:13]
	s_mov_b32 m0, s22
	ds_read_b128 v[162:165], v249 offset:49152
	ds_read_b128 v[166:169], v249 offset:50176
	ds_read_b128 v[170:173], v249 offset:51200
	ds_read_b128 v[174:177], v249 offset:52224
	ds_read_b128 v[178:181], v249 offset:53248
	ds_read_b128 v[182:185], v249 offset:54272
	ds_read_b128 v[186:189], v249 offset:55296
	ds_read_b128 v[190:193], v249 offset:56320
	global_load_lds_dwordx4 v[204:205], off
	s_add_i32 m0, s22, 0x2000
	s_add_u32 s22, s26, 0x160080
	v_lshl_add_u64 v[204:205], v[206:207], 0, s[12:13]
	s_addc_u32 s23, s27, 0
	s_add_i32 s26, s50, s7
	global_load_lds_dwordx4 v[204:205], off
	v_lshl_add_u64 v[204:205], s[22:23], 0, v[0:1]
	s_mov_b32 m0, s26
	s_nop 0
	global_load_lds_dwordx4 v[204:205], off
	v_lshl_add_u64 v[204:205], s[22:23], 0, v[194:195]
	s_add_i32 m0, s26, 0x2000
	s_nop 0
	global_load_lds_dwordx4 v[204:205], off
	v_lshl_add_u64 v[204:205], v[208:209], 0, s[12:13]
	s_mov_b32 m0, s35
	s_nop 0
	global_load_lds_dwordx4 v[204:205], off
	v_lshl_add_u64 v[204:205], v[210:211], 0, s[12:13]
	s_mov_b32 m0, s40
	s_nop 0
	global_load_lds_dwordx4 v[204:205], off
	s_waitcnt vmcnt(8)
	s_waitcnt lgkmcnt(0)
	s_setprio 1
	s_barrier
	v_mfma_f32_16x16x32_bf16 v[62:65], v[90:93], v[162:165], v[62:65]
	v_mfma_f32_16x16x32_bf16 v[62:65], v[102:105], v[166:169], v[62:65]
	v_mfma_f32_16x16x32_bf16 v[58:61], v[114:117], v[162:165], v[58:61]
	v_mfma_f32_16x16x32_bf16 v[58:61], v[126:129], v[166:169], v[58:61]
	v_mfma_f32_16x16x32_bf16 v[42:45], v[114:117], v[170:173], v[42:45]
	v_mfma_f32_16x16x32_bf16 v[42:45], v[126:129], v[174:177], v[42:45]
	v_mfma_f32_16x16x32_bf16 v[46:49], v[90:93], v[170:173], v[46:49]
	v_mfma_f32_16x16x32_bf16 v[46:49], v[102:105], v[174:177], v[46:49]
	v_mfma_f32_16x16x32_bf16 v[30:33], v[90:93], v[178:181], v[30:33]
	v_mfma_f32_16x16x32_bf16 v[30:33], v[102:105], v[182:185], v[30:33]
	v_mfma_f32_16x16x32_bf16 v[26:29], v[114:117], v[178:181], v[26:29]
	v_mfma_f32_16x16x32_bf16 v[26:29], v[126:129], v[182:185], v[26:29]
	v_mfma_f32_16x16x32_bf16 v[10:13], v[114:117], v[186:189], v[10:13]
	v_mfma_f32_16x16x32_bf16 v[10:13], v[126:129], v[190:193], v[10:13]
	v_mfma_f32_16x16x32_bf16 v[14:17], v[90:93], v[186:189], v[14:17]
	v_mfma_f32_16x16x32_bf16 v[14:17], v[102:105], v[190:193], v[14:17]
	v_mfma_f32_16x16x32_bf16 v[54:57], v[138:141], v[162:165], v[54:57]
	v_mfma_f32_16x16x32_bf16 v[54:57], v[142:145], v[166:169], v[54:57]
	v_mfma_f32_16x16x32_bf16 v[50:53], v[154:157], v[162:165], v[50:53]
	v_mfma_f32_16x16x32_bf16 v[50:53], v[158:161], v[166:169], v[50:53]
	v_mfma_f32_16x16x32_bf16 v[34:37], v[154:157], v[170:173], v[34:37]
	v_mfma_f32_16x16x32_bf16 v[34:37], v[158:161], v[174:177], v[34:37]
	v_mfma_f32_16x16x32_bf16 v[38:41], v[138:141], v[170:173], v[38:41]
	v_mfma_f32_16x16x32_bf16 v[38:41], v[142:145], v[174:177], v[38:41]
	v_mfma_f32_16x16x32_bf16 v[22:25], v[138:141], v[178:181], v[22:25]
	v_mfma_f32_16x16x32_bf16 v[22:25], v[142:145], v[182:185], v[22:25]
	v_mfma_f32_16x16x32_bf16 v[18:21], v[154:157], v[178:181], v[18:21]
	v_mfma_f32_16x16x32_bf16 v[18:21], v[158:161], v[182:185], v[18:21]
	v_mfma_f32_16x16x32_bf16 v[2:5], v[154:157], v[186:189], v[2:5]
	v_mfma_f32_16x16x32_bf16 v[2:5], v[158:161], v[190:193], v[2:5]
	v_mfma_f32_16x16x32_bf16 v[6:9], v[138:141], v[186:189], v[6:9]
	v_mfma_f32_16x16x32_bf16 v[6:9], v[142:145], v[190:193], v[6:9]
	s_barrier
	s_setprio 0
	s_add_i32 s48, s48, 2
	s_add_u32 s46, s46, 0x100
	s_addc_u32 s47, s47, 0
	s_cmpk_gt_u32 s48, 0x55
	s_mov_b64 s[22:23], s[24:25]
	s_cbranch_scc0 .LBB0_1007
	s_and_b64 vcc, exec, s[18:19]
	s_cbranch_vccz .LBB0_1010
	s_barrier
	s_setprio 1
